# SSD dt stage: one wait for its three loads; y_off group-norm weights requested before the cross-lane reduction (waited before use), wait covering 30 write-through stores removed
# speedup vs baseline: 1.0035x; 1.0014x over previous
; __device__ __forceinline__ void ssd_chunk_unit(LAS unsigned char* ldsb, int unit, const bf16* PROJ, bf16* XACT, const float* DTRAW, const float* conv_w, const float* conv_b, const float* dt_bias, const float* a_log, ...
;     ...
;         const int s = tid >> 2, hh = tid & 3, H = g * 4 + hh;
;         const float A = -__expf(a_log[H]);
;         const float raw = DTRAW[(size_t)(tok0 + s) * 8 + H] + dt_bias[H];
;         const float dtv = fmaxf(raw, 0.f) + log1pf(__expf(-fabsf(raw)));
;         float v = dtv * A;
; #pragma unroll
;         for (int o = 4; o < 64; o <<= 1) { const float y = __shfl_up(v, o); if (lane >= o) v += y; }
;         if (lane >= 60) WT[wave * 4 + hh] = v;
;         __syncthreads();
.LBB0_169:
	v_mov_b32_e32 v222, v208
	v_mov_b32_e32 v118, v209
	s_and_b32 s24, s55, 1
	s_lshl_b32 s63, s24, 2
	v_and_b32_e32 v6, 3, v118
	v_or_b32_e32 v4, s63, v6
	v_readlane_b32 s64, v235, 16
	v_lshlrev_b32_e32 v10, 2, v4
	v_readlane_b32 s65, v235, 17
	s_add_i32 s6, s55, 0xffffff00
	s_ashr_i32 s60, s6, 1
	s_lshl_b32 s12, s60, 7
	v_ashrrev_i32_e32 v5, 2, v118
	v_readlane_b32 s66, v235, 18
	global_load_dword v7, v10, s[64:65]
	v_readlane_b32 s67, v235, 19
	v_readlane_b32 s68, v235, 20
	v_readlane_b32 s69, v235, 21
	v_readlane_b32 s70, v235, 22
	v_readlane_b32 s71, v235, 23
	v_readlane_b32 s72, v235, 24
	v_readlane_b32 s73, v235, 25
	v_readlane_b32 s74, v235, 26
	v_readlane_b32 s75, v235, 27
	v_readlane_b32 s76, v235, 28
	v_readlane_b32 s77, v235, 29
	v_readlane_b32 s78, v235, 30
	v_readlane_b32 s79, v235, 31
	v_readlane_b32 s64, v235, 0
	v_readlane_b32 s78, v235, 14
	v_readlane_b32 s79, v235, 15
	s_mov_b32 s6, 0xbfb8aa3b
	v_readlane_b32 s65, v235, 1
	v_readlane_b32 s66, v235, 2
	v_readlane_b32 s67, v235, 3
	v_readlane_b32 s68, v235, 4
	v_readlane_b32 s69, v235, 5
	v_readlane_b32 s70, v235, 6
	v_readlane_b32 s71, v235, 7
	v_readlane_b32 s72, v235, 8
	v_readlane_b32 s73, v235, 9
	v_readlane_b32 s74, v235, 10
	v_readlane_b32 s75, v235, 11
	v_readlane_b32 s76, v235, 12
	v_readlane_b32 s77, v235, 13
	s_nop 0
	v_add_u32_e32 v2, s12, v5
	v_ashrrev_i32_e32 v3, 31, v2
	v_lshlrev_b64 v[2:3], 3, v[2:3]
	v_or_b32_e32 v2, v2, v4
	v_lshl_add_u64 v[8:9], v[2:3], 2, s[0:1]
	global_load_dword v8, v[8:9], off
	s_nop 0
	global_load_dword v9, v10, s[78:79]
	s_waitcnt vmcnt(0)
	v_mul_f32_e32 v7, 0x3fb8aa3b, v7
	v_exp_f32_e32 v7, v7
	v_add_f32_e32 v8, v8, v9
	v_max_f32_e32 v10, 0, v8
	v_mul_f32_e64 v8, |v8|, s6
	v_exp_f32_e32 v11, v8
	s_mov_b32 s6, 0x3f2aaaab
	v_add_f32_e32 v12, 1.0, v11
	v_add_f32_e32 v8, -1.0, v12
	v_sub_f32_e32 v9, v8, v12
	v_add_f32_e32 v9, 1.0, v9
	v_sub_f32_e32 v8, v11, v8
	v_add_f32_e32 v13, v8, v9
	v_frexp_mant_f32_e32 v8, v12
	v_cmp_gt_f32_e32 vcc, s6, v8
	v_cvt_f64_f32_e32 v[8:9], v12
	v_frexp_exp_i32_f64_e32 v8, v[8:9]
	v_subbrev_co_u32_e32 v8, vcc, 0, v8, vcc
	v_sub_u32_e32 v9, 0, v8
	v_ldexp_f32 v12, v12, v9
	v_ldexp_f32 v9, v13, v9
	v_add_f32_e32 v13, -1.0, v12
	v_add_f32_e32 v14, 1.0, v13
	v_sub_f32_e32 v14, v12, v14
	v_add_f32_e32 v14, v9, v14
	v_add_f32_e32 v15, v13, v14
	v_sub_f32_e32 v13, v15, v13
	v_sub_f32_e32 v13, v14, v13
	v_add_f32_e32 v14, 1.0, v12
	v_add_f32_e32 v16, -1.0, v14
	v_sub_f32_e32 v12, v12, v16
	v_add_f32_e32 v9, v9, v12
	v_add_f32_e32 v12, v14, v9
	v_sub_f32_e32 v14, v12, v14
	v_sub_f32_e32 v9, v9, v14
	v_rcp_f32_e32 v14, v12
	v_cvt_f32_i32_e32 v8, v8
	s_mov_b32 s6, 0x3f317218
	v_mul_f32_e32 v16, v15, v14
	v_mul_f32_e32 v17, v12, v16
	v_fma_f32 v18, v16, v12, -v17
	v_fmac_f32_e32 v18, v16, v9
	v_add_f32_e32 v19, v17, v18
	v_sub_f32_e32 v20, v15, v19
	v_sub_f32_e32 v15, v15, v20
	v_sub_f32_e32 v17, v19, v17
	v_sub_f32_e32 v15, v15, v19
	v_add_f32_e32 v13, v13, v15
	v_sub_f32_e32 v15, v17, v18
	v_add_f32_e32 v13, v15, v13
	v_add_f32_e32 v15, v20, v13
	v_mul_f32_e32 v17, v14, v15
	v_mul_f32_e32 v18, v12, v17
	v_fma_f32 v12, v17, v12, -v18
	v_fmac_f32_e32 v12, v17, v9
	v_sub_f32_e32 v9, v20, v15
	v_add_f32_e32 v9, v13, v9
	v_add_f32_e32 v13, v18, v12
	v_sub_f32_e32 v19, v15, v13
	v_sub_f32_e32 v15, v15, v19
	v_sub_f32_e32 v18, v13, v18
	v_sub_f32_e32 v13, v15, v13
	v_add_f32_e32 v9, v9, v13
	v_sub_f32_e32 v12, v18, v12
	v_add_f32_e32 v9, v12, v9
	v_add_f32_e32 v12, v16, v17
	v_add_f32_e32 v9, v19, v9
	v_sub_f32_e32 v13, v12, v16
	v_mul_f32_e32 v9, v14, v9
	v_sub_f32_e32 v13, v17, v13
	v_add_f32_e32 v9, v13, v9
	v_mul_f32_e32 v16, 0x3f317218, v8
	v_add_f32_e32 v13, v12, v9
	v_fma_f32 v17, v8, s6, -v16
	v_mul_f32_e32 v14, v13, v13
	v_fmac_f32_e32 v17, 0xb102e308, v8
	v_sub_f32_e32 v8, v13, v12
	v_fmamk_f32 v15, v14, 0x3e9b6dac, v1
	v_sub_f32_e32 v8, v9, v8
	v_add_f32_e32 v9, v16, v17
	v_fmaak_f32 v15, v14, v15, 0x3f2aaada
	v_sub_f32_e32 v12, v9, v16
	v_ldexp_f32 v16, v13, 1
	v_mul_f32_e32 v13, v13, v14
	v_mul_f32_e32 v13, v13, v15
	v_add_f32_e32 v14, v16, v13
	v_sub_f32_e32 v15, v14, v16
	v_ldexp_f32 v8, v8, 1
	v_sub_f32_e32 v13, v13, v15
	v_add_f32_e32 v8, v8, v13
	v_add_f32_e32 v13, v14, v8
	v_sub_f32_e32 v14, v13, v14
	v_sub_f32_e32 v8, v8, v14
	v_add_f32_e32 v14, v9, v13
	v_sub_f32_e32 v15, v14, v9
	v_sub_f32_e32 v16, v14, v15
	v_sub_f32_e32 v12, v17, v12
	v_sub_f32_e32 v9, v9, v16
	v_sub_f32_e32 v13, v13, v15
	v_add_f32_e32 v9, v13, v9
	v_add_f32_e32 v13, v12, v8
	v_sub_f32_e32 v15, v13, v12
	v_sub_f32_e32 v16, v13, v15
	v_sub_f32_e32 v12, v12, v16
	v_sub_f32_e32 v8, v8, v15
	v_add_f32_e32 v9, v13, v9
	v_add_f32_e32 v8, v8, v12
	v_add_f32_e32 v12, v14, v9
	v_sub_f32_e32 v13, v12, v14
	v_sub_f32_e32 v9, v9, v13
	v_add_f32_e32 v8, v8, v9
	s_mov_b32 s6, 0x7f800000
	v_add_f32_e32 v8, v12, v8
	v_cmp_neq_f32_e32 vcc, s6, v11
	s_mov_b32 s6, 0x33800000
	s_nop 0
	v_cndmask_b32_e32 v8, v210, v8, vcc
	v_cmp_ngt_f32_e32 vcc, -1.0, v11
	s_nop 1
	v_cndmask_b32_e32 v8, v211, v8, vcc
	v_cmp_neq_f32_e32 vcc, -1.0, v11
	s_nop 1
	v_cndmask_b32_e32 v8, v212, v8, vcc
	v_cmp_lt_f32_e64 vcc, |v11|, s6
	s_nop 1
	v_cndmask_b32_e32 v8, v8, v11, vcc
	v_cmp_lt_i32_e32 vcc, v215, v214
	v_add_f32_e32 v8, v10, v8
	v_mul_f32_e64 v9, v8, -v7
	v_cndmask_b32_e32 v10, v215, v213, vcc
	v_lshlrev_b32_e32 v10, 2, v10
	ds_bpermute_b32 v10, v10, v9
	v_cmp_gt_i32_e32 vcc, 4, v222
	s_waitcnt lgkmcnt(0)
	v_fma_f32 v7, v8, -v7, v10
	v_cndmask_b32_e32 v7, v7, v9, vcc
	v_cmp_lt_i32_e32 vcc, v216, v214
	s_nop 1
	v_cndmask_b32_e32 v9, v216, v213, vcc
	v_lshlrev_b32_e32 v9, 2, v9
	ds_bpermute_b32 v9, v9, v7
	v_cmp_gt_i32_e32 vcc, 8, v222
	s_waitcnt lgkmcnt(0)
	v_add_f32_e32 v9, v7, v9
	v_cndmask_b32_e32 v7, v9, v7, vcc
	v_cmp_lt_i32_e32 vcc, v217, v214
	s_nop 1
	v_cndmask_b32_e32 v9, v217, v213, vcc
	v_lshlrev_b32_e32 v9, 2, v9
	ds_bpermute_b32 v9, v9, v7
	v_cmp_gt_i32_e32 vcc, 16, v222
	s_waitcnt lgkmcnt(0)
	v_add_f32_e32 v9, v7, v9
	v_cndmask_b32_e32 v7, v9, v7, vcc
	v_cmp_lt_i32_e32 vcc, v218, v214
	s_nop 1
	v_cndmask_b32_e32 v9, v218, v213, vcc
	v_lshlrev_b32_e32 v9, 2, v9
	ds_bpermute_b32 v9, v9, v7
	v_cmp_lt_i32_e32 vcc, 59, v222
	s_waitcnt lgkmcnt(0)
	v_add_f32_e32 v9, v7, v9
	s_and_saveexec_b64 s[6:7], vcc
	v_lshl_add_u32 v10, v6, 2, s61
	ds_write_b32 v10, v9
	s_or_b64 exec, exec, s[6:7]
	v_cmp_gt_i32_e32 vcc, 32, v222
	s_waitcnt lgkmcnt(0)
	s_barrier
; __device__ __forceinline__ void ssd_chunk_unit(LAS unsigned char* ldsb, int unit, const bf16* PROJ, bf16* XACT, const float* DTRAW, const float* conv_w, const float* conv_b, const float* dt_bias, const float* a_log, ...
;     ...
;         float off = 0.f, tot = 0.f;
;         for (int w2 = 0; w2 < 8; ++w2) { const float wv = WT[w2 * 4 + hh]; tot += wv; if (w2 < wave) off += wv; }
;         v += off;
;         DTT[tid] = dtv; ACST[tid] = v; WTAB[hh * 128 + s] = __expf(tot - v); __hip_atomic_store(&ACS[(size_t)(tok0 + s) * 8 + H], v, __ATOMIC_RELAXED, __HIP_MEMORY_SCOPE_AGENT);
;         if (s == 127) __hip_atomic_store(&CDEC[bc * 8 + H], __expf(v), __ATOMIC_RELAXED, __HIP_MEMORY_SCOPE_AGENT);
	v_cndmask_b32_e32 v7, v9, v7, vcc
	v_lshl_add_u32 v9, v6, 2, 0
	v_add_u32_e32 v9, 0x1b000, v9
	ds_read2_b32 v[10:11], v9 offset1:4
	ds_read2_b32 v[12:13], v9 offset0:8 offset1:12
	v_readlane_b32 s6, v235, 60
	v_readlane_b32 s7, v235, 61
	v_lshlrev_b32_e32 v6, 9, v6
	s_waitcnt lgkmcnt(1)
	v_add_f32_e32 v10, 0, v10
	v_cndmask_b32_e64 v14, v10, 0, s[6:7]
	v_readlane_b32 s6, v235, 62
	v_add_f32_e32 v10, v10, v11
	v_add_f32_e32 v11, v11, v14
	v_readlane_b32 s7, v235, 63
	s_waitcnt lgkmcnt(0)
	v_add_f32_e32 v10, v10, v12
	v_lshl_add_u64 v[2:3], v[2:3], 2, s[52:53]
	v_cndmask_b32_e64 v11, v14, v11, s[6:7]
	v_readlane_b32 s6, v234, 0
	v_add_f32_e32 v12, v12, v11
	v_readlane_b32 s7, v234, 1
	s_nop 1
	v_cndmask_b32_e64 v11, v11, v12, s[6:7]
	v_readlane_b32 s6, v234, 2
	v_add_f32_e32 v12, v10, v13
	v_add_f32_e32 v10, v13, v11
	v_readlane_b32 s7, v234, 3
	s_nop 1
	v_cndmask_b32_e64 v13, v11, v10, s[6:7]
	ds_read2_b32 v[10:11], v9 offset0:16 offset1:20
	v_readlane_b32 s6, v234, 4
	v_readlane_b32 s7, v234, 5
	s_waitcnt lgkmcnt(0)
	v_add_f32_e32 v12, v12, v10
	v_add_f32_e32 v10, v10, v13
	v_cndmask_b32_e64 v10, v13, v10, s[6:7]
	v_readlane_b32 s6, v234, 6
	v_add_f32_e32 v12, v12, v11
	v_add_f32_e32 v11, v11, v10
	v_readlane_b32 s7, v234, 7
	s_nop 1
	v_cndmask_b32_e64 v13, v10, v11, s[6:7]
	ds_read2_b32 v[10:11], v9 offset0:24 offset1:28
	v_readlane_b32 s6, v234, 8
	v_readlane_b32 s7, v234, 9
	s_waitcnt lgkmcnt(0)
	v_add_f32_e32 v9, v12, v10
	v_add_f32_e32 v10, v10, v13
	v_cndmask_b32_e64 v10, v13, v10, s[6:7]
	v_readlane_b32 s6, v234, 10
	v_add_f32_e32 v9, v9, v11
	v_add_f32_e32 v11, v11, v10
	v_readlane_b32 s7, v234, 11
	s_nop 1
	v_cndmask_b32_e64 v10, v10, v11, s[6:7]
	v_add_f32_e32 v7, v7, v10
	v_lshl_add_u32 v10, v118, 2, 0
	v_add_u32_e32 v11, 0x1a000, v10
	ds_write_b32 v11, v8
	v_add_u32_e32 v8, 0x19800, v10
	ds_write_b32 v8, v7
	v_sub_f32_e32 v8, v9, v7
	v_mul_f32_e32 v8, 0x3fb8aa3b, v8
	v_exp_f32_e32 v8, v8
	v_lshlrev_b32_e32 v9, 2, v5
	s_movk_i32 s6, 0x7f
	v_add3_u32 v6, s14, v6, v9
	v_cmp_eq_u32_e32 vcc, s6, v5
	ds_write_b32 v6, v8
	global_store_dword v[2:3], v7, off sc1
	s_and_saveexec_b64 s[6:7], vcc
	s_cbranch_execz .LBB0_173
	v_mul_f32_e32 v2, 0x3fb8aa3b, v7
	v_exp_f32_e32 v5, v2
	v_lshl_or_b32 v2, s60, 3, v4
	v_ashrrev_i32_e32 v3, 31, v2
	v_lshl_add_u64 v[2:3], v[2:3], 2, s[82:83]
	global_store_dword v[2:3], v5, off sc1

; __device__ __forceinline__ void yoff_unit(const float* d_skip, const float* gnorm, LAS unsigned char* ldsb, int unit, const bf16* XACT, const bf16* PROJ, const float* ACS, const bf16* PREVT,
;                                           const bf16* YD, bf16* MIXB, int lane, int wave) {
;     ...
;     bf16x8 cf[8];
;     { unsigned co = (unsigned)(tok0 + 32 * lt + r) * 1024u + (unsigned)(768 + g * 128 + 8 * hi); asm volatile("" : "+v"(co)); const bf16* cp = XACT + co;
; #pragma unroll
;       for (int ks = 0; ks < 8; ++ks) cf[ks] = ldg8(cp + 16 * ks); }
;     float eav[16], ssq[16];
;     unsigned ypk[2][16];
; #pragma unroll
;     for (int i = 0; i < 16; ++i) ssq[i] = 0.f;
; #pragma unroll
;     for (int hsel = 0; hsel < 2; ++hsel) {
;         const int H = g * 4 + 2 * hpair + hsel; unsigned pvo = (unsigned)(bc * 8 + H) * 8192u + (unsigned)(8 * hi); asm volatile("" : "+v"(pvo)); const bf16* pv = PREVT + pvo;
;         bf16x8 b0[8], b1[8]; unsigned ev[16];
; #pragma unroll
;         for (int ks = 0; ks < 8; ++ks) { b0[ks] = ldg8(pv + (2 * r) * 128 + 16 * ks); b1[ks] = ldg8(pv + (2 * r + 1) * 128 + 16 * ks); }
;         { const unsigned vo = (tb * 8u + (unsigned)H) * 4u;
; #pragma unroll
;           for (int i = 0; i < 16; ++i) ev[i] = (unsigned)__builtin_amdgcn_raw_buffer_load_b32(rsA, (int)vo, ((i & 3) + 8 * (i >> 2)) * 32, 0); }
;         const float dsk = d_skip[H];
;         __builtin_amdgcn_sched_barrier(0);
;         f32x16 Y0 = zero16(), Y1 = zero16();
; #pragma unroll
;         for (int ks = 0; ks < 8; ++ks) { Y0 = MFMA32(cf[ks], b0[ks], Y0); Y1 = MFMA32(cf[ks], b1[ks], Y1); }
; #pragma unroll
;         for (int i = 0; i < 16; ++i) eav[i] = __expf(__uint_as_float(ev[i]));
;         {
;             const unsigned col = (unsigned)(H * 64 + 2 * r);
;             const unsigned voF = (tb * 512u + col) * 2u, voX = (tb * 1024u + col) * 2u, voP = (tb * (unsigned)PS + (unsigned)OZ + col) * 2u;
;             unsigned yo[16], xsv[16], zv[16];
; #pragma unroll
;             for (int i = 0; i < 16; ++i) { const int ro = (i & 3) + 8 * (i >> 2);
;                 yo[i] = (unsigned)__builtin_amdgcn_raw_buffer_load_b32(rsF, (int)voF, ro * 1024, 2);
;                 xsv[i] = (unsigned)__builtin_amdgcn_raw_buffer_load_b32(rsX, (int)voX, ro * 2048, 2);
;                 zv[i] = (unsigned)__builtin_amdgcn_raw_buffer_load_b32(rsP, (int)voP, ro * (PS * 2), 2); }
.LBB0_466:
	s_ashr_i32 s5, s94, 1
	s_lshl_b32 s6, s5, 7
	s_and_b32 s4, s94, 1
	s_or_b32 s6, s6, s23
	v_or_b32_e32 v2, s6, v1
	v_lshl_or_b32 v3, s4, 7, v151
	v_readlane_b32 s24, v235, 48
	v_lshl_or_b32 v110, v2, 10, v3
	v_readlane_b32 s25, v235, 49
	s_lshl_b32 s4, s4, 2
	s_add_i32 s4, s4, s29
	v_lshl_add_u64 v[2:3], v[110:111], 1, s[24:25]
	v_lshl_or_b32 v95, s5, 16, v150
	global_load_dwordx4 v[62:65], v[2:3], off
	global_load_dwordx4 v[58:61], v[2:3], off offset:32
	global_load_dwordx4 v[54:57], v[2:3], off offset:64
	global_load_dwordx4 v[50:53], v[2:3], off offset:96
	global_load_dwordx4 v[46:49], v[2:3], off offset:128
	global_load_dwordx4 v[42:45], v[2:3], off offset:160
	global_load_dwordx4 v[38:41], v[2:3], off offset:192
	global_load_dwordx4 v[34:37], v[2:3], off offset:224
	v_or_b32_e32 v2, s6, v149
	s_movk_i32 s5, 0x900
	v_lshl_add_u32 v110, s4, 13, v95
	v_lshlrev_b32_e32 v148, 5, v2
	v_lshlrev_b32_e32 v115, 10, v2
	v_mul_lo_u32 v2, v2, s5
	v_or_b32_e32 v163, 0x300, v2
	v_lshl_add_u64 v[6:7], v[110:111], 1, v[112:113]
	global_load_dwordx4 v[2:5], v[6:7], off
	global_load_dwordx4 v[18:21], v[6:7], off offset:256
	global_load_dwordx4 v[22:25], v[6:7], off offset:32
	global_load_dwordx4 v[90:93], v[6:7], off offset:288
	global_load_dwordx4 v[26:29], v[6:7], off offset:64
	global_load_dwordx4 v[86:89], v[6:7], off offset:320
	global_load_dwordx4 v[30:33], v[6:7], off offset:96
	global_load_dwordx4 v[82:85], v[6:7], off offset:352
	global_load_dwordx4 v[96:99], v[6:7], off offset:128
	global_load_dwordx4 v[78:81], v[6:7], off offset:384
	global_load_dwordx4 v[100:103], v[6:7], off offset:160
	global_load_dwordx4 v[74:77], v[6:7], off offset:416
	global_load_dwordx4 v[104:107], v[6:7], off offset:192
	global_load_dwordx4 v[70:73], v[6:7], off offset:448
	global_load_dwordx4 v[116:119], v[6:7], off offset:224
	global_load_dwordx4 v[66:69], v[6:7], off offset:480
	s_lshl_b32 s5, s4, 2
	v_add_u32_e32 v6, s5, v148
	s_movk_i32 s6, 0x60
	s_movk_i32 s24, 0x100
	s_movk_i32 s25, 0x120
	s_movk_i32 s26, 0x140
	s_movk_i32 s27, 0x160
	s_movk_i32 s85, 0x240
	s_movk_i32 s3, 0x260
	s_movk_i32 s7, 0x300
	buffer_load_dword v120, v6, s[52:55], 0 offen
	buffer_load_dword v121, v6, s[52:55], 32 offen
	buffer_load_dword v122, v6, s[52:55], 64 offen
	buffer_load_dword v123, v6, s[52:55], s6 offen
	buffer_load_dword v124, v6, s[52:55], s24 offen
	buffer_load_dword v125, v6, s[52:55], s25 offen
	buffer_load_dword v141, v6, s[52:55], s26 offen
	buffer_load_dword v142, v6, s[52:55], s27 offen
	buffer_load_dword v143, v6, s[52:55], s95 offen
	buffer_load_dword v144, v6, s[52:55], s21 offen
	buffer_load_dword v145, v6, s[52:55], s85 offen
	buffer_load_dword v146, v6, s[52:55], s3 offen
	buffer_load_dword v147, v6, s[52:55], s7 offen
	buffer_load_dword v165, v6, s[52:55], s34 offen
	buffer_load_dword v166, v6, s[52:55], s35 offen
	buffer_load_dword v167, v6, s[52:55], s36 offen
	v_readlane_b32 s64, v235, 16
	v_mov_b32_e32 v164, s5
	v_readlane_b32 s66, v235, 18
	v_readlane_b32 s67, v235, 19
	v_readlane_b32 s65, v235, 17
	v_readlane_b32 s68, v235, 20
	v_readlane_b32 s69, v235, 21
	v_readlane_b32 s70, v235, 22
	v_readlane_b32 s71, v235, 23
	global_load_dword v94, v164, s[66:67]
	v_readlane_b32 s72, v235, 24
	v_readlane_b32 s73, v235, 25
	v_readlane_b32 s74, v235, 26
	v_readlane_b32 s75, v235, 27
	v_readlane_b32 s76, v235, 28
	v_readlane_b32 s77, v235, 29
	v_readlane_b32 s78, v235, 30
	v_readlane_b32 s79, v235, 31
	s_waitcnt vmcnt(32)
	v_mfma_f32_32x32x16_bf16 v[2:17], v[62:65], v[2:5], 0
	v_lshl_or_b32 v114, s4, 6, v152
	v_add_lshl_u32 v168, v163, v114, 1
	s_movk_i32 s5, 0x400
	s_movk_i32 s65, 0xc00
	s_movk_i32 s69, 0x2000
	s_movk_i32 s64, 0x1200
	s_movk_i32 s68, 0x3600
	s_waitcnt vmcnt(30)
	v_mfma_f32_32x32x16_bf16 v[2:17], v[58:61], v[22:25], v[2:17]
	s_mov_b32 s70, 0xa200
	s_mov_b32 s72, 0xb400
	s_mov_b32 s74, 0xc600
	s_movk_i32 s71, 0x2800
	s_movk_i32 s73, 0x2c00
	s_movk_i32 s76, 0x4400
	s_movk_i32 s79, 0x4c00
	s_waitcnt vmcnt(28)
	v_mfma_f32_32x32x16_bf16 v[2:17], v[54:57], v[26:29], v[2:17]
	s_mov_b32 s75, 0x12000
	s_mov_b32 s77, 0x13200
	s_mov_b32 s78, 0x14400
	s_waitcnt vmcnt(26)
	v_mfma_f32_32x32x16_bf16 v[2:17], v[50:53], v[30:33], v[2:17]
	s_waitcnt vmcnt(24)
	v_mfma_f32_32x32x16_bf16 v[2:17], v[46:49], v[96:99], v[2:17]
	v_lshl_add_u32 v96, v114, 1, v115
	v_add_u32_e32 v110, v96, v115
	buffer_load_dword v169, v96, s[12:15], 0 offen nt
	buffer_load_dword v170, v96, s[12:15], s5 offen nt
	buffer_load_dword v171, v96, s[12:15], s46 offen nt
	buffer_load_dword v172, v96, s[12:15], s65 offen nt
	buffer_load_dword v173, v96, s[12:15], s69 offen nt
	buffer_load_dword v132, v96, s[12:15], s62 offen nt
	buffer_load_dword v108, v96, s[12:15], s82 offen nt
	buffer_load_dword v126, v96, s[12:15], s49 offen nt
	buffer_load_dword v174, v168, s[16:19], 0 offen nt
	s_waitcnt vmcnt(31)
	v_mfma_f32_32x32x16_bf16 v[2:17], v[42:45], v[100:103], v[2:17]
	buffer_load_dword v175, v168, s[16:19], s64 offen nt
	buffer_load_dword v176, v168, s[16:19], s49 offen nt
	buffer_load_dword v177, v168, s[16:19], s68 offen nt
	buffer_load_dword v178, v168, s[16:19], s63 offen nt
	buffer_load_dword v127, v168, s[16:19], s70 offen nt
	buffer_load_dword v128, v168, s[16:19], s72 offen nt
	buffer_load_dword v130, v168, s[16:19], s74 offen nt
	v_mfma_f32_32x32x16_bf16 v[18:33], v[62:65], v[18:21], 0
	s_waitcnt vmcnt(36)
	v_mfma_f32_32x32x16_bf16 v[2:17], v[38:41], v[104:107], v[2:17]
	v_mfma_f32_32x32x16_bf16 v[18:33], v[58:61], v[90:93], v[18:33]
	s_waitcnt vmcnt(34)
; __device__ __forceinline__ float silu_f(float v) { return v * __builtin_amdgcn_rcpf(1.f + __expf(-v)); }
; #define MFMA32(a, b, c) __builtin_amdgcn_mfma_f32_32x32x16_bf16((a), (b), (c), 0, 0, 0)
; __device__ __forceinline__ void yoff_unit(const float* d_skip, const float* gnorm, LAS unsigned char* ldsb, int unit, const bf16* XACT, const bf16* PROJ, const float* ACS, const bf16* PREVT,
;                                           const bf16* YD, bf16* MIXB, int lane, int wave) {
;     ...
;         for (int ks = 0; ks < 8; ++ks) { Y0 = MFMA32(cf[ks], b0[ks], Y0); Y1 = MFMA32(cf[ks], b1[ks], Y1); }
; #pragma unroll
;         for (int i = 0; i < 16; ++i) eav[i] = __expf(__uint_as_float(ev[i]));
;         {
;             const unsigned col = (unsigned)(H * 64 + 2 * r);
;             const unsigned voF = (tb * 512u + col) * 2u, voX = (tb * 1024u + col) * 2u, voP = (tb * (unsigned)PS + (unsigned)OZ + col) * 2u;
;             unsigned yo[16], xsv[16], zv[16];
; #pragma unroll
;             for (int i = 0; i < 16; ++i) { const int ro = (i & 3) + 8 * (i >> 2);
;                 yo[i] = (unsigned)__builtin_amdgcn_raw_buffer_load_b32(rsF, (int)voF, ro * 1024, 2);
;                 xsv[i] = (unsigned)__builtin_amdgcn_raw_buffer_load_b32(rsX, (int)voX, ro * 2048, 2);
;                 zv[i] = (unsigned)__builtin_amdgcn_raw_buffer_load_b32(rsP, (int)voP, ro * (PS * 2), 2); }
;             __builtin_amdgcn_sched_barrier(0);
; #pragma unroll
;             for (int i = 0; i < 16; ++i) {
;                 const float y0 = (__uint_as_float(yo[i] << 16) + eav[i] * Y0[i] + dsk * __uint_as_float(xsv[i] << 16)) * silu_f(__uint_as_float(zv[i] << 16));
;                 const float y1 = (__uint_as_float(yo[i] & 0xffff0000u) + eav[i] * Y1[i] + dsk * __uint_as_float(xsv[i] & 0xffff0000u)) * silu_f(__uint_as_float(zv[i] & 0xffff0000u));
;                 ssq[i] += y0 * y0 + y1 * y1; ypk[hsel][i] = pkbf(y0, y1);
	v_mfma_f32_32x32x16_bf16 v[2:17], v[34:37], v[116:119], v[2:17]
	buffer_load_dword v117, v110, s[8:11], 0 offen nt
	buffer_load_dword v119, v110, s[8:11], s46 offen nt
	buffer_load_dword v179, v110, s[8:11], s48 offen nt
	buffer_load_dword v180, v110, s[8:11], s56 offen nt
	buffer_load_dword v181, v110, s[8:11], s62 offen nt
	buffer_load_dword v140, v110, s[8:11], s82 offen nt
	buffer_load_dword v129, v110, s[8:11], s93 offen nt
	buffer_load_dword v109, v110, s[8:11], s63 offen nt
	buffer_load_dword v139, v96, s[12:15], s71 offen nt
	buffer_load_dword v131, v96, s[12:15], s73 offen nt
	buffer_load_dword v134, v96, s[12:15], s76 offen nt
	buffer_load_dword v105, v96, s[12:15], s79 offen nt
	buffer_load_dword v101, v96, s[12:15], s39 offen nt
	buffer_load_dword v99, v96, s[12:15], s42 offen nt
	buffer_load_dword v98, v96, s[12:15], s45 offen nt
	buffer_load_dword v97, v96, s[12:15], s58 offen nt
	buffer_load_dword v138, v110, s[8:11], s20 offen nt
	buffer_load_dword v133, v110, s[8:11], s84 offen nt
	buffer_load_dword v135, v110, s[8:11], s28 offen nt
	buffer_load_dword v106, v110, s[8:11], s37 offen nt
	buffer_load_dword v103, v110, s[8:11], s40 offen nt
	buffer_load_dword v100, v110, s[8:11], s43 offen nt
	buffer_load_dword v93, v110, s[8:11], s47 offen nt
	buffer_load_dword v91, v110, s[8:11], s59 offen nt
	buffer_load_dword v137, v168, s[16:19], s75 offen nt
	buffer_load_dword v136, v168, s[16:19], s77 offen nt
	v_mfma_f32_32x32x16_bf16 v[18:33], v[54:57], v[86:89], v[18:33]
	buffer_load_dword v110, v168, s[16:19], s78 offen nt
	buffer_load_dword v107, v168, s[16:19], s38 offen nt
	buffer_load_dword v104, v168, s[16:19], s41 offen nt
	buffer_load_dword v102, v168, s[16:19], s44 offen nt
	buffer_load_dword v89, v168, s[16:19], s57 offen nt
	buffer_load_dword v87, v168, s[16:19], s83 offen nt
	s_waitcnt vmcnt(62)
	v_mul_f32_e32 v86, 0x3fb8aa3b, v120
	v_exp_f32_e32 v116, v86
	v_mul_f32_e32 v86, 0x3fb8aa3b, v121
	v_exp_f32_e32 v118, v86
	v_mfma_f32_32x32x16_bf16 v[18:33], v[50:53], v[82:85], v[18:33]
	v_mul_f32_e32 v82, 0x3fb8aa3b, v122
	v_exp_f32_e32 v120, v82
	s_waitcnt vmcnt(61)
	v_mul_f32_e32 v82, 0x3fb8aa3b, v123
	v_exp_f32_e32 v96, v82
	s_waitcnt vmcnt(60)
	v_mul_f32_e32 v82, 0x3fb8aa3b, v124
	v_exp_f32_e32 v92, v82
	s_waitcnt vmcnt(59)
	v_mul_f32_e32 v82, 0x3fb8aa3b, v125
	v_mfma_f32_32x32x16_bf16 v[18:33], v[46:49], v[78:81], v[18:33]
	s_waitcnt vmcnt(58)
	v_mul_f32_e32 v78, 0x3fb8aa3b, v141
	v_exp_f32_e32 v90, v82
	v_exp_f32_e32 v88, v78
	s_waitcnt vmcnt(57)
	v_mul_f32_e32 v78, 0x3fb8aa3b, v142
	v_exp_f32_e32 v86, v78
	s_waitcnt vmcnt(56)
	v_mul_f32_e32 v78, 0x3fb8aa3b, v143
	v_exp_f32_e32 v84, v78
	v_mfma_f32_32x32x16_bf16 v[18:33], v[42:45], v[74:77], v[18:33]
	s_waitcnt vmcnt(55)
	v_mul_f32_e32 v74, 0x3fb8aa3b, v144
	v_exp_f32_e32 v82, v74
	s_waitcnt vmcnt(54)
	v_mul_f32_e32 v74, 0x3fb8aa3b, v145
	v_exp_f32_e32 v80, v74
	s_waitcnt vmcnt(53)
	v_mul_f32_e32 v74, 0x3fb8aa3b, v146
	v_exp_f32_e32 v78, v74
	s_waitcnt vmcnt(52)
	v_mul_f32_e32 v74, 0x3fb8aa3b, v147
	v_mfma_f32_32x32x16_bf16 v[18:33], v[38:41], v[70:73], v[18:33]
	s_waitcnt vmcnt(51)
	v_mul_f32_e32 v70, 0x3fb8aa3b, v165
	v_exp_f32_e32 v76, v74
	v_exp_f32_e32 v74, v70
	s_waitcnt vmcnt(50)
	v_mul_f32_e32 v70, 0x3fb8aa3b, v166
	v_exp_f32_e32 v72, v70
	s_waitcnt vmcnt(49)
	v_mul_f32_e32 v70, 0x3fb8aa3b, v167
	v_exp_f32_e32 v70, v70
	v_mfma_f32_32x32x16_bf16 v[18:33], v[34:37], v[66:69], v[18:33]
	s_waitcnt vmcnt(39)
	v_lshlrev_b32_e32 v122, 16, v174
	v_and_b32_e32 v123, 0xffff0000, v174
	v_mul_f32_e32 v71, 0xbfb8aa3b, v122
	v_mov_b32_e32 v142, v2
	v_mul_f32_e32 v2, 0xbfb8aa3b, v123
	v_exp_f32_e32 v71, v71
	v_exp_f32_e32 v2, v2
	v_lshlrev_b32_e32 v66, 16, v169
	v_and_b32_e32 v67, 0xffff0000, v169
	v_add_f32_e32 v71, 1.0, v71
	v_add_f32_e32 v2, 1.0, v2
	v_rcp_f32_e32 v124, v71
	v_rcp_f32_e32 v125, v2
	v_mov_b32_e32 v143, v18
	s_waitcnt vmcnt(31)
	v_lshlrev_b32_e32 v68, 16, v117
	v_and_b32_e32 v69, 0xffff0000, v117
	v_pk_fma_f32 v[66:67], v[116:117], v[142:143], v[66:67] op_sel_hi:[0,1,1]
	v_pk_fma_f32 v[66:67], v[94:95], v[68:69], v[66:67] op_sel_hi:[0,1,1]
	v_pk_mul_f32 v[68:69], v[124:125], v[122:123]
	v_lshlrev_b32_e32 v122, 16, v175
	v_and_b32_e32 v123, 0xffff0000, v175
	v_mul_f32_e32 v2, 0xbfb8aa3b, v122
	v_mov_b32_e32 v18, v3
	v_mul_f32_e32 v3, 0xbfb8aa3b, v123
	v_exp_f32_e32 v2, v2
	v_exp_f32_e32 v3, v3
	v_pk_mul_f32 v[116:117], v[66:67], v[68:69]
	v_lshlrev_b32_e32 v66, 16, v170
	v_add_f32_e32 v2, 1.0, v2
	v_add_f32_e32 v3, 1.0, v3
	v_rcp_f32_e32 v2, v2
	v_rcp_f32_e32 v3, v3
	v_and_b32_e32 v67, 0xffff0000, v170
	s_waitcnt vmcnt(30)
	v_lshlrev_b32_e32 v68, 16, v119
	v_and_b32_e32 v69, 0xffff0000, v119
	v_pk_fma_f32 v[18:19], v[118:119], v[18:19], v[66:67] op_sel_hi:[0,1,1]
	v_lshlrev_b32_e32 v66, 16, v176
	v_and_b32_e32 v67, 0xffff0000, v176
	v_pk_fma_f32 v[18:19], v[94:95], v[68:69], v[18:19] op_sel_hi:[0,1,1]
	v_pk_mul_f32 v[2:3], v[2:3], v[122:123]
	v_mul_f32_e32 v68, 0xbfb8aa3b, v66
	v_mov_b32_e32 v122, v4
	v_mul_f32_e32 v4, 0xbfb8aa3b, v67
	v_exp_f32_e32 v68, v68
	v_exp_f32_e32 v4, v4
	v_pk_mul_f32 v[118:119], v[18:19], v[2:3]
	v_lshlrev_b32_e32 v2, 16, v171
	v_add_f32_e32 v68, 1.0, v68
	v_add_f32_e32 v4, 1.0, v4
	v_rcp_f32_e32 v68, v68
	v_rcp_f32_e32 v69, v4
	v_and_b32_e32 v3, 0xffff0000, v171
	v_mov_b32_e32 v123, v20
	s_waitcnt vmcnt(29)
; __device__ __forceinline__ float silu_f(float v) { return v * __builtin_amdgcn_rcpf(1.f + __expf(-v)); }
; __device__ __forceinline__ void yoff_unit(const float* d_skip, const float* gnorm, LAS unsigned char* ldsb, int unit, const bf16* XACT, const bf16* PROJ, const float* ACS, const bf16* PREVT,
;                                           const bf16* YD, bf16* MIXB, int lane, int wave) {
;     ...
;             for (int i = 0; i < 16; ++i) {
;                 const float y0 = (__uint_as_float(yo[i] << 16) + eav[i] * Y0[i] + dsk * __uint_as_float(xsv[i] << 16)) * silu_f(__uint_as_float(zv[i] << 16));
;                 const float y1 = (__uint_as_float(yo[i] & 0xffff0000u) + eav[i] * Y1[i] + dsk * __uint_as_float(xsv[i] & 0xffff0000u)) * silu_f(__uint_as_float(zv[i] & 0xffff0000u));
;                 ssq[i] += y0 * y0 + y1 * y1; ypk[hsel][i] = pkbf(y0, y1);
;             }
	v_lshlrev_b32_e32 v18, 16, v179
	v_and_b32_e32 v19, 0xffff0000, v179
	v_pk_fma_f32 v[2:3], v[120:121], v[122:123], v[2:3] op_sel_hi:[0,1,1]
	v_pk_fma_f32 v[2:3], v[94:95], v[18:19], v[2:3] op_sel_hi:[0,1,1]
	v_pk_mul_f32 v[18:19], v[68:69], v[66:67]
	v_lshlrev_b32_e32 v66, 16, v177
	v_and_b32_e32 v67, 0xffff0000, v177
	v_mul_f32_e32 v4, 0xbfb8aa3b, v66
	v_mov_b32_e32 v20, v5
	v_mul_f32_e32 v5, 0xbfb8aa3b, v67
	v_exp_f32_e32 v4, v4
	v_exp_f32_e32 v5, v5
	v_pk_mul_f32 v[120:121], v[2:3], v[18:19]
	v_lshlrev_b32_e32 v2, 16, v172
	v_add_f32_e32 v4, 1.0, v4
	v_add_f32_e32 v5, 1.0, v5
	v_rcp_f32_e32 v4, v4
	v_rcp_f32_e32 v5, v5
	v_and_b32_e32 v3, 0xffff0000, v172
	s_waitcnt vmcnt(28)
	v_lshlrev_b32_e32 v18, 16, v180
	v_and_b32_e32 v19, 0xffff0000, v180
	s_waitcnt vmcnt(16)
	v_pk_fma_f32 v[2:3], v[96:97], v[20:21], v[2:3] op_sel_hi:[0,1,1]
	v_pk_fma_f32 v[2:3], v[94:95], v[18:19], v[2:3] op_sel_hi:[0,1,1]
	v_pk_mul_f32 v[4:5], v[4:5], v[66:67]
	v_mov_b32_e32 v66, v6
	v_pk_mul_f32 v[122:123], v[2:3], v[4:5]
	v_lshlrev_b32_e32 v2, 16, v173
	v_and_b32_e32 v3, 0xffff0000, v173
	v_mov_b32_e32 v67, v22
	v_lshlrev_b32_e32 v4, 16, v181
	v_lshlrev_b32_e32 v18, 16, v178
	v_and_b32_e32 v5, 0xffff0000, v181
	v_and_b32_e32 v19, 0xffff0000, v178
	s_waitcnt vmcnt(9)
	v_pk_fma_f32 v[2:3], v[92:93], v[66:67], v[2:3] op_sel_hi:[0,1,1]
	v_mul_f32_e32 v20, 0xbfb8aa3b, v18
	v_pk_fma_f32 v[2:3], v[94:95], v[4:5], v[2:3] op_sel_hi:[0,1,1]
	v_mul_f32_e32 v4, 0xbfb8aa3b, v19
	v_exp_f32_e32 v20, v20
	v_exp_f32_e32 v4, v4
	v_mov_b32_e32 v22, v7
	s_or_b32 s4, s4, 1
	v_add_f32_e32 v20, 1.0, v20
	v_add_f32_e32 v4, 1.0, v4
	v_rcp_f32_e32 v20, v20
	v_rcp_f32_e32 v21, v4
	s_nop 0
	v_pk_mul_f32 v[4:5], v[20:21], v[18:19]
	s_nop 0
	v_pk_mul_f32 v[124:125], v[2:3], v[4:5]
	v_lshlrev_b32_e32 v2, 16, v126
	v_and_b32_e32 v3, 0xffff0000, v126
	v_lshlrev_b32_e32 v4, 16, v140
	v_lshlrev_b32_e32 v18, 16, v127
	v_and_b32_e32 v5, 0xffff0000, v140
	v_and_b32_e32 v19, 0xffff0000, v127
	s_waitcnt vmcnt(8)
	v_pk_fma_f32 v[2:3], v[90:91], v[22:23], v[2:3] op_sel_hi:[0,1,1]
	v_mul_f32_e32 v6, 0xbfb8aa3b, v18
	v_pk_fma_f32 v[2:3], v[94:95], v[4:5], v[2:3] op_sel_hi:[0,1,1]
	v_mul_f32_e32 v4, 0xbfb8aa3b, v19
	v_exp_f32_e32 v6, v6
	v_exp_f32_e32 v4, v4
	v_mov_b32_e32 v20, v8
	v_mov_b32_e32 v21, v24
	v_add_f32_e32 v6, 1.0, v6
	v_add_f32_e32 v4, 1.0, v4
	v_rcp_f32_e32 v6, v6
	v_rcp_f32_e32 v7, v4
	v_mov_b32_e32 v24, v9
	v_pk_mul_f32 v[4:5], v[6:7], v[18:19]
	s_nop 0
	v_pk_mul_f32 v[126:127], v[2:3], v[4:5]
	v_lshlrev_b32_e32 v2, 16, v139
	v_and_b32_e32 v3, 0xffff0000, v139
	v_lshlrev_b32_e32 v4, 16, v129
	v_lshlrev_b32_e32 v6, 16, v128
	v_and_b32_e32 v5, 0xffff0000, v129
	v_and_b32_e32 v7, 0xffff0000, v128
	s_waitcnt vmcnt(1)
	v_pk_fma_f32 v[2:3], v[88:89], v[20:21], v[2:3] op_sel_hi:[0,1,1]
	v_mul_f32_e32 v18, 0xbfb8aa3b, v6
	v_pk_fma_f32 v[2:3], v[94:95], v[4:5], v[2:3] op_sel_hi:[0,1,1]
	v_mul_f32_e32 v4, 0xbfb8aa3b, v7
	v_exp_f32_e32 v18, v18
	v_exp_f32_e32 v4, v4
	v_add_f32_e32 v18, 1.0, v18
	v_add_f32_e32 v4, 1.0, v4
	v_rcp_f32_e32 v18, v18
	v_rcp_f32_e32 v19, v4
	s_nop 0
	v_pk_mul_f32 v[4:5], v[18:19], v[6:7]
	s_nop 0
	v_pk_mul_f32 v[128:129], v[2:3], v[4:5]
	v_lshlrev_b32_e32 v2, 16, v131
	v_and_b32_e32 v3, 0xffff0000, v131
	v_lshlrev_b32_e32 v4, 16, v138
	v_lshlrev_b32_e32 v6, 16, v130
	v_and_b32_e32 v5, 0xffff0000, v138
	v_and_b32_e32 v7, 0xffff0000, v130
	s_waitcnt vmcnt(0)
	v_pk_fma_f32 v[2:3], v[86:87], v[24:25], v[2:3] op_sel_hi:[0,1,1]
	v_mul_f32_e32 v8, 0xbfb8aa3b, v6
	v_pk_fma_f32 v[2:3], v[94:95], v[4:5], v[2:3] op_sel_hi:[0,1,1]
	v_mul_f32_e32 v4, 0xbfb8aa3b, v7
	v_exp_f32_e32 v8, v8
	v_exp_f32_e32 v4, v4
	v_mov_b32_e32 v18, v10
	v_mov_b32_e32 v19, v26
	v_add_f32_e32 v8, 1.0, v8
	v_add_f32_e32 v4, 1.0, v4
	v_rcp_f32_e32 v8, v8
	v_rcp_f32_e32 v9, v4
	v_mov_b32_e32 v26, v11
	v_mov_b32_e32 v10, v12
	v_mov_b32_e32 v11, v28
	v_pk_mul_f32 v[4:5], v[8:9], v[6:7]
	v_lshlrev_b32_e32 v6, 16, v137
	v_pk_mul_f32 v[130:131], v[2:3], v[4:5]
	v_lshlrev_b32_e32 v2, 16, v132
	v_and_b32_e32 v3, 0xffff0000, v132
	v_lshlrev_b32_e32 v4, 16, v133
	v_and_b32_e32 v5, 0xffff0000, v133
	v_and_b32_e32 v7, 0xffff0000, v137
	v_pk_fma_f32 v[2:3], v[84:85], v[18:19], v[2:3] op_sel_hi:[0,1,1]
	v_mul_f32_e32 v8, 0xbfb8aa3b, v6
	v_pk_fma_f32 v[2:3], v[94:95], v[4:5], v[2:3] op_sel_hi:[0,1,1]
	v_mul_f32_e32 v4, 0xbfb8aa3b, v7
	v_exp_f32_e32 v8, v8
	v_exp_f32_e32 v4, v4
	v_mov_b32_e32 v28, v13
	v_add_f32_e32 v8, 1.0, v8
	v_add_f32_e32 v4, 1.0, v4
	v_rcp_f32_e32 v8, v8
	v_rcp_f32_e32 v9, v4
	s_nop 0
	v_pk_mul_f32 v[4:5], v[8:9], v[6:7]
	s_nop 0
	v_pk_mul_f32 v[132:133], v[2:3], v[4:5]
	v_lshlrev_b32_e32 v2, 16, v134
	v_and_b32_e32 v3, 0xffff0000, v134
	v_lshlrev_b32_e32 v4, 16, v135
	v_lshlrev_b32_e32 v6, 16, v136
	v_and_b32_e32 v5, 0xffff0000, v135
	v_and_b32_e32 v7, 0xffff0000, v136
	v_pk_fma_f32 v[2:3], v[82:83], v[26:27], v[2:3] op_sel_hi:[0,1,1]
	v_mul_f32_e32 v8, 0xbfb8aa3b, v6
	v_pk_fma_f32 v[2:3], v[94:95], v[4:5], v[2:3] op_sel_hi:[0,1,1]
	v_mul_f32_e32 v4, 0xbfb8aa3b, v7
	v_exp_f32_e32 v8, v8
	v_exp_f32_e32 v4, v4
	v_add_f32_e32 v8, 1.0, v8
	v_add_f32_e32 v4, 1.0, v4
	v_rcp_f32_e32 v8, v8
	v_rcp_f32_e32 v9, v4
	s_nop 0
	v_pk_mul_f32 v[4:5], v[8:9], v[6:7]
	s_nop 0
	v_pk_mul_f32 v[134:135], v[2:3], v[4:5]
	v_lshlrev_b32_e32 v2, 16, v108
	v_and_b32_e32 v3, 0xffff0000, v108
	v_lshlrev_b32_e32 v4, 16, v109
	v_lshlrev_b32_e32 v6, 16, v110
	v_and_b32_e32 v5, 0xffff0000, v109
	v_and_b32_e32 v7, 0xffff0000, v110
	v_pk_fma_f32 v[2:3], v[80:81], v[10:11], v[2:3] op_sel_hi:[0,1,1]
	v_mul_f32_e32 v8, 0xbfb8aa3b, v6
	v_pk_fma_f32 v[2:3], v[94:95], v[4:5], v[2:3] op_sel_hi:[0,1,1]
	v_mul_f32_e32 v4, 0xbfb8aa3b, v7
; __device__ __forceinline__ float silu_f(float v) { return v * __builtin_amdgcn_rcpf(1.f + __expf(-v)); }
; __device__ __forceinline__ void yoff_unit(const float* d_skip, const float* gnorm, LAS unsigned char* ldsb, int unit, const bf16* XACT, const bf16* PROJ, const float* ACS, const bf16* PREVT,
;                                           const bf16* YD, bf16* MIXB, int lane, int wave) {
;     ...
;     for (int hsel = 0; hsel < 2; ++hsel) {
;         const int H = g * 4 + 2 * hpair + hsel; unsigned pvo = (unsigned)(bc * 8 + H) * 8192u + (unsigned)(8 * hi); asm volatile("" : "+v"(pvo)); const bf16* pv = PREVT + pvo;
;         bf16x8 b0[8], b1[8]; unsigned ev[16];
; #pragma unroll
;         for (int ks = 0; ks < 8; ++ks) { b0[ks] = ldg8(pv + (2 * r) * 128 + 16 * ks); b1[ks] = ldg8(pv + (2 * r + 1) * 128 + 16 * ks); }
;         { const unsigned vo = (tb * 8u + (unsigned)H) * 4u;
; #pragma unroll
;           for (int i = 0; i < 16; ++i) ev[i] = (unsigned)__builtin_amdgcn_raw_buffer_load_b32(rsA, (int)vo, ((i & 3) + 8 * (i >> 2)) * 32, 0); }
;         const float dsk = d_skip[H];
;         __builtin_amdgcn_sched_barrier(0);
;         f32x16 Y0 = zero16(), Y1 = zero16();
; #pragma unroll
;         for (int ks = 0; ks < 8; ++ks) { Y0 = MFMA32(cf[ks], b0[ks], Y0); Y1 = MFMA32(cf[ks], b1[ks], Y1); }
; #pragma unroll
;         for (int i = 0; i < 16; ++i) eav[i] = __expf(__uint_as_float(ev[i]));
;         {
;             const unsigned col = (unsigned)(H * 64 + 2 * r);
;             const unsigned voF = (tb * 512u + col) * 2u, voX = (tb * 1024u + col) * 2u, voP = (tb * (unsigned)PS + (unsigned)OZ + col) * 2u;
;             unsigned yo[16], xsv[16], zv[16];
; #pragma unroll
;             for (int i = 0; i < 16; ++i) { const int ro = (i & 3) + 8 * (i >> 2);
;                 yo[i] = (unsigned)__builtin_amdgcn_raw_buffer_load_b32(rsF, (int)voF, ro * 1024, 2);
;                 xsv[i] = (unsigned)__builtin_amdgcn_raw_buffer_load_b32(rsX, (int)voX, ro * 2048, 2);
;                 zv[i] = (unsigned)__builtin_amdgcn_raw_buffer_load_b32(rsP, (int)voP, ro * (PS * 2), 2); }
;             __builtin_amdgcn_sched_barrier(0);
; #pragma unroll
;             for (int i = 0; i < 16; ++i) {
;                 const float y0 = (__uint_as_float(yo[i] << 16) + eav[i] * Y0[i] + dsk * __uint_as_float(xsv[i] << 16)) * silu_f(__uint_as_float(zv[i] << 16));
	v_exp_f32_e32 v8, v8
	v_exp_f32_e32 v4, v4
	v_mov_b32_e32 v10, v14
	v_mov_b32_e32 v11, v30
	v_add_f32_e32 v8, 1.0, v8
	v_add_f32_e32 v4, 1.0, v4
	v_rcp_f32_e32 v8, v8
	v_rcp_f32_e32 v9, v4
	v_mov_b32_e32 v30, v15
	v_lshl_add_u32 v110, s4, 13, v95
	v_pk_mul_f32 v[4:5], v[8:9], v[6:7]
	v_lshlrev_b32_e32 v6, 16, v107
	v_pk_mul_f32 v[136:137], v[2:3], v[4:5]
	v_lshlrev_b32_e32 v2, 16, v105
	v_and_b32_e32 v3, 0xffff0000, v105
	v_lshlrev_b32_e32 v4, 16, v106
	v_and_b32_e32 v5, 0xffff0000, v106
	v_and_b32_e32 v7, 0xffff0000, v107
	v_pk_fma_f32 v[2:3], v[78:79], v[28:29], v[2:3] op_sel_hi:[0,1,1]
	v_mul_f32_e32 v8, 0xbfb8aa3b, v6
	v_pk_fma_f32 v[2:3], v[94:95], v[4:5], v[2:3] op_sel_hi:[0,1,1]
	v_mul_f32_e32 v4, 0xbfb8aa3b, v7
	v_exp_f32_e32 v8, v8
	v_exp_f32_e32 v4, v4
	v_add_f32_e32 v8, 1.0, v8
	v_add_f32_e32 v4, 1.0, v4
	v_rcp_f32_e32 v8, v8
	v_rcp_f32_e32 v9, v4
	s_nop 0
	v_pk_mul_f32 v[4:5], v[8:9], v[6:7]
	s_nop 0
	v_pk_mul_f32 v[138:139], v[2:3], v[4:5]
	v_lshlrev_b32_e32 v2, 16, v101
	v_and_b32_e32 v3, 0xffff0000, v101
	v_lshlrev_b32_e32 v4, 16, v103
	v_lshlrev_b32_e32 v6, 16, v104
	v_and_b32_e32 v5, 0xffff0000, v103
	v_and_b32_e32 v7, 0xffff0000, v104
	v_pk_fma_f32 v[2:3], v[76:77], v[10:11], v[2:3] op_sel_hi:[0,1,1]
	v_mul_f32_e32 v8, 0xbfb8aa3b, v6
	v_pk_fma_f32 v[2:3], v[94:95], v[4:5], v[2:3] op_sel_hi:[0,1,1]
	v_mul_f32_e32 v4, 0xbfb8aa3b, v7
	v_exp_f32_e32 v8, v8
	v_exp_f32_e32 v4, v4
	v_mov_b32_e32 v10, v16
	v_mov_b32_e32 v11, v32
	v_add_f32_e32 v8, 1.0, v8
	v_add_f32_e32 v4, 1.0, v4
	v_rcp_f32_e32 v8, v8
	v_rcp_f32_e32 v9, v4
	v_mov_b32_e32 v32, v17
	v_pk_mul_f32 v[4:5], v[8:9], v[6:7]
	s_nop 0
	v_pk_mul_f32 v[140:141], v[2:3], v[4:5]
	v_lshlrev_b32_e32 v2, 16, v99
	v_and_b32_e32 v3, 0xffff0000, v99
	v_lshlrev_b32_e32 v4, 16, v100
	v_lshlrev_b32_e32 v6, 16, v102
	v_and_b32_e32 v5, 0xffff0000, v100
	v_and_b32_e32 v7, 0xffff0000, v102
	v_pk_fma_f32 v[2:3], v[74:75], v[30:31], v[2:3] op_sel_hi:[0,1,1]
	v_mul_f32_e32 v8, 0xbfb8aa3b, v6
	v_pk_fma_f32 v[2:3], v[94:95], v[4:5], v[2:3] op_sel_hi:[0,1,1]
	v_mul_f32_e32 v4, 0xbfb8aa3b, v7
	v_exp_f32_e32 v8, v8
	v_exp_f32_e32 v4, v4
	v_add_f32_e32 v8, 1.0, v8
	v_add_f32_e32 v4, 1.0, v4
	v_rcp_f32_e32 v8, v8
	v_rcp_f32_e32 v9, v4
	s_nop 0
	v_pk_mul_f32 v[4:5], v[8:9], v[6:7]
	s_nop 0
	v_pk_mul_f32 v[142:143], v[2:3], v[4:5]
	v_lshlrev_b32_e32 v2, 16, v98
	v_and_b32_e32 v3, 0xffff0000, v98
	v_lshlrev_b32_e32 v4, 16, v93
	v_lshlrev_b32_e32 v6, 16, v89
	v_and_b32_e32 v5, 0xffff0000, v93
	v_and_b32_e32 v7, 0xffff0000, v89
	v_pk_fma_f32 v[2:3], v[72:73], v[10:11], v[2:3] op_sel_hi:[0,1,1]
	v_mul_f32_e32 v8, 0xbfb8aa3b, v6
	v_pk_fma_f32 v[2:3], v[94:95], v[4:5], v[2:3] op_sel_hi:[0,1,1]
	v_mul_f32_e32 v4, 0xbfb8aa3b, v7
	v_exp_f32_e32 v8, v8
	v_exp_f32_e32 v4, v4
	v_add_f32_e32 v8, 1.0, v8
	v_add_f32_e32 v4, 1.0, v4
	v_rcp_f32_e32 v8, v8
	v_rcp_f32_e32 v9, v4
	s_nop 0
	v_pk_mul_f32 v[4:5], v[8:9], v[6:7]
	s_nop 0
	v_pk_mul_f32 v[144:145], v[2:3], v[4:5]
	v_lshlrev_b32_e32 v2, 16, v97
	v_and_b32_e32 v3, 0xffff0000, v97
	v_lshlrev_b32_e32 v4, 16, v91
	v_lshlrev_b32_e32 v6, 16, v87
	v_and_b32_e32 v5, 0xffff0000, v91
	v_and_b32_e32 v7, 0xffff0000, v87
	v_pk_fma_f32 v[2:3], v[70:71], v[32:33], v[2:3] op_sel_hi:[0,1,1]
	v_mul_f32_e32 v8, 0xbfb8aa3b, v6
	v_pk_fma_f32 v[2:3], v[94:95], v[4:5], v[2:3] op_sel_hi:[0,1,1]
	v_mul_f32_e32 v4, 0xbfb8aa3b, v7
	v_exp_f32_e32 v8, v8
	v_exp_f32_e32 v4, v4
	v_add_f32_e32 v8, 1.0, v8
	v_add_f32_e32 v4, 1.0, v4
	v_rcp_f32_e32 v8, v8
	v_rcp_f32_e32 v9, v4
	s_nop 0
	v_pk_mul_f32 v[4:5], v[8:9], v[6:7]
	v_lshl_add_u64 v[6:7], v[110:111], 1, v[112:113]
	v_pk_mul_f32 v[146:147], v[2:3], v[4:5]
	global_load_dwordx4 v[2:5], v[6:7], off
	global_load_dwordx4 v[18:21], v[6:7], off offset:256
	global_load_dwordx4 v[30:33], v[6:7], off offset:32
	global_load_dwordx4 v[90:93], v[6:7], off offset:288
	global_load_dwordx4 v[98:101], v[6:7], off offset:64
	global_load_dwordx4 v[86:89], v[6:7], off offset:320
	global_load_dwordx4 v[102:105], v[6:7], off offset:96
	global_load_dwordx4 v[82:85], v[6:7], off offset:352
	global_load_dwordx4 v[106:109], v[6:7], off offset:128
	global_load_dwordx4 v[78:81], v[6:7], off offset:384
	global_load_dwordx4 v[94:97], v[6:7], off offset:160
	global_load_dwordx4 v[74:77], v[6:7], off offset:416
	global_load_dwordx4 v[26:29], v[6:7], off offset:192
	global_load_dwordx4 v[70:73], v[6:7], off offset:448
	global_load_dwordx4 v[22:25], v[6:7], off offset:224
	global_load_dwordx4 v[66:69], v[6:7], off offset:480
	v_lshl_add_u32 v6, s4, 2, v148
	buffer_load_dword v176, v6, s[52:55], 0 offen
	buffer_load_dword v175, v6, s[52:55], 32 offen
	buffer_load_dword v171, v6, s[52:55], 64 offen
	buffer_load_dword v172, v6, s[52:55], s6 offen
	buffer_load_dword v173, v6, s[52:55], s24 offen
	buffer_load_dword v174, v6, s[52:55], s25 offen
	buffer_load_dword v168, v6, s[52:55], s26 offen
	buffer_load_dword v169, v6, s[52:55], s27 offen
	buffer_load_dword v170, v6, s[52:55], s95 offen
	buffer_load_dword v165, v6, s[52:55], s21 offen
	buffer_load_dword v166, v6, s[52:55], s85 offen
	buffer_load_dword v167, v6, s[52:55], s3 offen
	buffer_load_dword v177, v6, s[52:55], s7 offen
	buffer_load_dword v178, v6, s[52:55], s34 offen
	buffer_load_dword v179, v6, s[52:55], s35 offen
	buffer_load_dword v180, v6, s[52:55], s36 offen
	global_load_dword v148, v164, s[66:67] offset:4
	s_waitcnt vmcnt(32)
	v_mfma_f32_32x32x16_bf16 v[2:17], v[62:65], v[2:5], 0
	v_lshl_or_b32 v110, s4, 6, v152
	v_add_lshl_u32 v181, v163, v110, 1
	s_waitcnt vmcnt(30)
	v_mfma_f32_32x32x16_bf16 v[2:17], v[58:61], v[30:33], v[2:17]
	s_waitcnt vmcnt(28)
; __device__ __forceinline__ float silu_f(float v) { return v * __builtin_amdgcn_rcpf(1.f + __expf(-v)); }
; #define MFMA32(a, b, c) __builtin_amdgcn_mfma_f32_32x32x16_bf16((a), (b), (c), 0, 0, 0)
; __device__ __forceinline__ void yoff_unit(const float* d_skip, const float* gnorm, LAS unsigned char* ldsb, int unit, const bf16* XACT, const bf16* PROJ, const float* ACS, const bf16* PREVT,
;                                           const bf16* YD, bf16* MIXB, int lane, int wave) {
;     ...
;         f32x16 Y0 = zero16(), Y1 = zero16();
; #pragma unroll
;         for (int ks = 0; ks < 8; ++ks) { Y0 = MFMA32(cf[ks], b0[ks], Y0); Y1 = MFMA32(cf[ks], b1[ks], Y1); }
; #pragma unroll
;         for (int i = 0; i < 16; ++i) eav[i] = __expf(__uint_as_float(ev[i]));
;         {
;             const unsigned col = (unsigned)(H * 64 + 2 * r);
;             const unsigned voF = (tb * 512u + col) * 2u, voX = (tb * 1024u + col) * 2u, voP = (tb * (unsigned)PS + (unsigned)OZ + col) * 2u;
;             unsigned yo[16], xsv[16], zv[16];
; #pragma unroll
;             for (int i = 0; i < 16; ++i) { const int ro = (i & 3) + 8 * (i >> 2);
;                 yo[i] = (unsigned)__builtin_amdgcn_raw_buffer_load_b32(rsF, (int)voF, ro * 1024, 2);
;                 xsv[i] = (unsigned)__builtin_amdgcn_raw_buffer_load_b32(rsX, (int)voX, ro * 2048, 2);
;                 zv[i] = (unsigned)__builtin_amdgcn_raw_buffer_load_b32(rsP, (int)voP, ro * (PS * 2), 2); }
;             __builtin_amdgcn_sched_barrier(0);
; #pragma unroll
;             for (int i = 0; i < 16; ++i) {
;                 const float y0 = (__uint_as_float(yo[i] << 16) + eav[i] * Y0[i] + dsk * __uint_as_float(xsv[i] << 16)) * silu_f(__uint_as_float(zv[i] << 16));
;                 const float y1 = (__uint_as_float(yo[i] & 0xffff0000u) + eav[i] * Y1[i] + dsk * __uint_as_float(xsv[i] & 0xffff0000u)) * silu_f(__uint_as_float(zv[i] & 0xffff0000u));
;                 ssq[i] += y0 * y0 + y1 * y1; ypk[hsel][i] = pkbf(y0, y1);
	v_mfma_f32_32x32x16_bf16 v[2:17], v[54:57], v[98:101], v[2:17]
	v_lshl_add_u32 v99, v110, 1, v115
	s_waitcnt vmcnt(26)
	v_mfma_f32_32x32x16_bf16 v[2:17], v[50:53], v[102:105], v[2:17]
	v_add_u32_e32 v102, v99, v115
	s_waitcnt vmcnt(24)
	v_mfma_f32_32x32x16_bf16 v[2:17], v[46:49], v[106:109], v[2:17]
	s_waitcnt vmcnt(22)
	v_mfma_f32_32x32x16_bf16 v[2:17], v[42:45], v[94:97], v[2:17]
	buffer_load_dword v183, v99, s[12:15], 0 offen nt
	buffer_load_dword v184, v99, s[12:15], s5 offen nt
	buffer_load_dword v185, v99, s[12:15], s46 offen nt
	buffer_load_dword v186, v99, s[12:15], s65 offen nt
	buffer_load_dword v187, v99, s[12:15], s69 offen nt
	buffer_load_dword v100, v99, s[12:15], s62 offen nt
	buffer_load_dword v96, v99, s[12:15], s82 offen nt
	buffer_load_dword v109, v99, s[12:15], s49 offen nt
	buffer_load_dword v188, v181, s[16:19], 0 offen nt
	buffer_load_dword v189, v181, s[16:19], s64 offen nt
	buffer_load_dword v190, v181, s[16:19], s49 offen nt
	buffer_load_dword v191, v181, s[16:19], s68 offen nt
	buffer_load_dword v192, v181, s[16:19], s63 offen nt
	buffer_load_dword v163, v181, s[16:19], s70 offen nt
	buffer_load_dword v106, v181, s[16:19], s72 offen nt
	buffer_load_dword v103, v181, s[16:19], s74 offen nt
	buffer_load_dword v193, v102, s[8:11], 0 offen nt
	buffer_load_dword v194, v102, s[8:11], s46 offen nt
	buffer_load_dword v195, v102, s[8:11], s48 offen nt
	buffer_load_dword v196, v102, s[8:11], s56 offen nt
	buffer_load_dword v197, v102, s[8:11], s62 offen nt
	buffer_load_dword v164, v102, s[8:11], s82 offen nt
	buffer_load_dword v107, v102, s[8:11], s93 offen nt
	buffer_load_dword v97, v102, s[8:11], s63 offen nt
	s_waitcnt vmcnt(44)
	v_mfma_f32_32x32x16_bf16 v[2:17], v[38:41], v[26:29], v[2:17]
	s_waitcnt vmcnt(42)
	v_mfma_f32_32x32x16_bf16 v[2:17], v[34:37], v[22:25], v[2:17]
	v_mfma_f32_32x32x16_bf16 v[18:33], v[62:65], v[18:21], 0
	buffer_load_dword v108, v99, s[12:15], s71 offen nt
	buffer_load_dword v104, v99, s[12:15], s73 offen nt
	buffer_load_dword v98, v99, s[12:15], s76 offen nt
	buffer_load_dword v95, v99, s[12:15], s79 offen nt
	buffer_load_dword v94, v99, s[12:15], s39 offen nt
	buffer_load_dword v65, v99, s[12:15], s42 offen nt
	buffer_load_dword v64, v99, s[12:15], s45 offen nt
	buffer_load_dword v63, v99, s[12:15], s58 offen nt
	v_mfma_f32_32x32x16_bf16 v[18:33], v[58:61], v[90:93], v[18:33]
	buffer_load_dword v105, v102, s[8:11], s20 offen nt
	buffer_load_dword v101, v102, s[8:11], s84 offen nt
	buffer_load_dword v93, v102, s[8:11], s28 offen nt
	buffer_load_dword v92, v102, s[8:11], s37 offen nt
	buffer_load_dword v91, v102, s[8:11], s40 offen nt
	buffer_load_dword v90, v102, s[8:11], s43 offen nt
	buffer_load_dword v61, v102, s[8:11], s47 offen nt
	buffer_load_dword v59, v102, s[8:11], s59 offen nt
	v_mfma_f32_32x32x16_bf16 v[18:33], v[54:57], v[86:89], v[18:33]
	buffer_load_dword v102, v181, s[16:19], s75 offen nt
	buffer_load_dword v99, v181, s[16:19], s77 offen nt
	buffer_load_dword v89, v181, s[16:19], s78 offen nt
	buffer_load_dword v88, v181, s[16:19], s38 offen nt
	buffer_load_dword v87, v181, s[16:19], s41 offen nt
	buffer_load_dword v86, v181, s[16:19], s44 offen nt
	buffer_load_dword v57, v181, s[16:19], s57 offen nt
	buffer_load_dword v55, v181, s[16:19], s83 offen nt
	s_waitcnt vmcnt(62)
	v_mul_f32_e32 v54, 0x3fb8aa3b, v176
	v_exp_f32_e32 v176, v54
	v_mul_f32_e32 v54, 0x3fb8aa3b, v175
	v_exp_f32_e32 v182, v54
	v_mfma_f32_32x32x16_bf16 v[18:33], v[50:53], v[82:85], v[18:33]
	v_mul_f32_e32 v50, 0x3fb8aa3b, v171
	v_exp_f32_e32 v82, v50
	s_waitcnt vmcnt(61)
	v_mul_f32_e32 v50, 0x3fb8aa3b, v172
	v_exp_f32_e32 v62, v50
	s_waitcnt vmcnt(60)
	v_mul_f32_e32 v50, 0x3fb8aa3b, v173
	v_exp_f32_e32 v60, v50
	s_waitcnt vmcnt(59)
	v_mul_f32_e32 v50, 0x3fb8aa3b, v174
	v_mfma_f32_32x32x16_bf16 v[18:33], v[46:49], v[78:81], v[18:33]
	s_waitcnt vmcnt(58)
	v_mul_f32_e32 v46, 0x3fb8aa3b, v168
	v_exp_f32_e32 v58, v50
	v_exp_f32_e32 v56, v46
	s_waitcnt vmcnt(57)
	v_mul_f32_e32 v46, 0x3fb8aa3b, v169
	v_exp_f32_e32 v54, v46
	s_waitcnt vmcnt(56)
	v_mul_f32_e32 v46, 0x3fb8aa3b, v170
	v_exp_f32_e32 v52, v46
	v_mfma_f32_32x32x16_bf16 v[18:33], v[42:45], v[74:77], v[18:33]
	s_waitcnt vmcnt(55)
	v_mul_f32_e32 v42, 0x3fb8aa3b, v165
	v_exp_f32_e32 v50, v42
	s_waitcnt vmcnt(54)
	v_mul_f32_e32 v42, 0x3fb8aa3b, v166
	v_exp_f32_e32 v48, v42
	s_waitcnt vmcnt(53)
	v_mul_f32_e32 v42, 0x3fb8aa3b, v167
	v_exp_f32_e32 v46, v42
	s_waitcnt vmcnt(52)
	v_mul_f32_e32 v42, 0x3fb8aa3b, v177
	v_mfma_f32_32x32x16_bf16 v[18:33], v[38:41], v[70:73], v[18:33]
	s_waitcnt vmcnt(51)
	v_mul_f32_e32 v38, 0x3fb8aa3b, v178
	v_exp_f32_e32 v44, v42
	v_exp_f32_e32 v42, v38
	s_waitcnt vmcnt(50)
	v_mul_f32_e32 v38, 0x3fb8aa3b, v179
	v_exp_f32_e32 v40, v38
	s_waitcnt vmcnt(49)
	v_mul_f32_e32 v38, 0x3fb8aa3b, v180
	v_exp_f32_e32 v38, v38
	v_mfma_f32_32x32x16_bf16 v[18:33], v[34:37], v[66:69], v[18:33]
	s_waitcnt vmcnt(39)
	v_lshlrev_b32_e32 v66, 16, v188
	v_and_b32_e32 v67, 0xffff0000, v188
	v_mul_f32_e32 v39, 0xbfb8aa3b, v66
	v_mov_b32_e32 v70, v2
	v_mul_f32_e32 v2, 0xbfb8aa3b, v67
	v_exp_f32_e32 v39, v39
	v_exp_f32_e32 v2, v2
	v_lshlrev_b32_e32 v34, 16, v183
	v_and_b32_e32 v35, 0xffff0000, v183
	v_add_f32_e32 v39, 1.0, v39
	v_add_f32_e32 v2, 1.0, v2
	v_rcp_f32_e32 v68, v39
	v_rcp_f32_e32 v69, v2
	v_mov_b32_e32 v71, v18
	s_waitcnt vmcnt(31)
	v_lshlrev_b32_e32 v36, 16, v193
	v_and_b32_e32 v37, 0xffff0000, v193
	v_pk_fma_f32 v[34:35], v[176:177], v[70:71], v[34:35] op_sel_hi:[0,1,1]
	v_pk_fma_f32 v[34:35], v[148:149], v[36:37], v[34:35] op_sel_hi:[0,1,1]
	v_pk_mul_f32 v[36:37], v[68:69], v[66:67]
	v_lshlrev_b32_e32 v68, 16, v189
	v_and_b32_e32 v69, 0xffff0000, v189
	v_mul_f32_e32 v2, 0xbfb8aa3b, v68
	v_mov_b32_e32 v18, v3
	v_mul_f32_e32 v3, 0xbfb8aa3b, v69
	v_pk_mul_f32 v[34:35], v[34:35], v[36:37]
	v_lshlrev_b32_e32 v36, 16, v184
	v_and_b32_e32 v37, 0xffff0000, v184
	v_exp_f32_e32 v2, v2
	v_exp_f32_e32 v3, v3
	s_waitcnt vmcnt(30)
; __device__ __forceinline__ float silu_f(float v) { return v * __builtin_amdgcn_rcpf(1.f + __expf(-v)); }
; __device__ __forceinline__ void yoff_unit(const float* d_skip, const float* gnorm, LAS unsigned char* ldsb, int unit, const bf16* XACT, const bf16* PROJ, const float* ACS, const bf16* PREVT,
;                                           const bf16* YD, bf16* MIXB, int lane, int wave) {
;     ...
;             for (int i = 0; i < 16; ++i) {
;                 const float y0 = (__uint_as_float(yo[i] << 16) + eav[i] * Y0[i] + dsk * __uint_as_float(xsv[i] << 16)) * silu_f(__uint_as_float(zv[i] << 16));
;                 const float y1 = (__uint_as_float(yo[i] & 0xffff0000u) + eav[i] * Y1[i] + dsk * __uint_as_float(xsv[i] & 0xffff0000u)) * silu_f(__uint_as_float(zv[i] & 0xffff0000u));
;                 ssq[i] += y0 * y0 + y1 * y1; ypk[hsel][i] = pkbf(y0, y1);
	v_lshlrev_b32_e32 v66, 16, v194
	v_and_b32_e32 v67, 0xffff0000, v194
	v_pk_fma_f32 v[18:19], v[182:183], v[18:19], v[36:37] op_sel_hi:[0,1,1]
	v_pk_fma_f32 v[18:19], v[148:149], v[66:67], v[18:19] op_sel_hi:[0,1,1]
	v_lshlrev_b32_e32 v66, 16, v190
	v_and_b32_e32 v67, 0xffff0000, v190
	v_mul_f32_e32 v39, 0xbfb8aa3b, v66
	v_mov_b32_e32 v70, v4
	v_mul_f32_e32 v4, 0xbfb8aa3b, v67
	v_add_f32_e32 v2, 1.0, v2
	v_add_f32_e32 v3, 1.0, v3
	v_exp_f32_e32 v39, v39
	v_exp_f32_e32 v4, v4
	v_rcp_f32_e32 v2, v2
	v_rcp_f32_e32 v3, v3
	v_add_f32_e32 v39, 1.0, v39
	v_add_f32_e32 v4, 1.0, v4
	v_mov_b32_e32 v71, v20
	v_pk_mul_f32 v[2:3], v[2:3], v[68:69]
	v_rcp_f32_e32 v68, v39
	v_rcp_f32_e32 v69, v4
	v_pk_mul_f32 v[2:3], v[18:19], v[2:3]
	v_lshlrev_b32_e32 v18, 16, v185
	v_and_b32_e32 v19, 0xffff0000, v185
	s_waitcnt vmcnt(29)
	v_lshlrev_b32_e32 v36, 16, v195
	v_and_b32_e32 v37, 0xffff0000, v195
	v_pk_fma_f32 v[18:19], v[82:83], v[70:71], v[18:19] op_sel_hi:[0,1,1]
	v_pk_fma_f32 v[18:19], v[148:149], v[36:37], v[18:19] op_sel_hi:[0,1,1]
	v_pk_mul_f32 v[36:37], v[68:69], v[66:67]
	v_lshlrev_b32_e32 v68, 16, v191
	v_and_b32_e32 v69, 0xffff0000, v191
	v_mul_f32_e32 v4, 0xbfb8aa3b, v68
	v_mov_b32_e32 v20, v5
	v_mul_f32_e32 v5, 0xbfb8aa3b, v69
	v_pk_mul_f32 v[18:19], v[18:19], v[36:37]
	v_lshlrev_b32_e32 v36, 16, v186
	v_and_b32_e32 v37, 0xffff0000, v186
	v_exp_f32_e32 v4, v4
	v_exp_f32_e32 v5, v5
	s_waitcnt vmcnt(28)
	v_lshlrev_b32_e32 v66, 16, v196
	v_and_b32_e32 v67, 0xffff0000, v196
	s_waitcnt vmcnt(16)
	v_pk_fma_f32 v[20:21], v[62:63], v[20:21], v[36:37] op_sel_hi:[0,1,1]
	v_pk_fma_f32 v[20:21], v[148:149], v[66:67], v[20:21] op_sel_hi:[0,1,1]
	v_lshlrev_b32_e32 v66, 16, v192
	v_and_b32_e32 v67, 0xffff0000, v192
	v_mul_f32_e32 v39, 0xbfb8aa3b, v66
	v_mov_b32_e32 v70, v6
	v_mul_f32_e32 v6, 0xbfb8aa3b, v67
	v_add_f32_e32 v4, 1.0, v4
	v_add_f32_e32 v5, 1.0, v5
	v_exp_f32_e32 v39, v39
	v_exp_f32_e32 v6, v6
	v_rcp_f32_e32 v4, v4
	v_rcp_f32_e32 v5, v5
	v_add_f32_e32 v39, 1.0, v39
	v_add_f32_e32 v6, 1.0, v6
	v_mov_b32_e32 v71, v22
	v_pk_mul_f32 v[4:5], v[4:5], v[68:69]
	v_rcp_f32_e32 v68, v39
	v_rcp_f32_e32 v69, v6
	v_pk_mul_f32 v[4:5], v[20:21], v[4:5]
	v_lshlrev_b32_e32 v20, 16, v187
	v_and_b32_e32 v21, 0xffff0000, v187
	v_lshlrev_b32_e32 v36, 16, v197
	v_and_b32_e32 v37, 0xffff0000, v197
	s_waitcnt vmcnt(9)
	v_pk_fma_f32 v[20:21], v[60:61], v[70:71], v[20:21] op_sel_hi:[0,1,1]
	v_pk_fma_f32 v[20:21], v[148:149], v[36:37], v[20:21] op_sel_hi:[0,1,1]
	v_pk_mul_f32 v[36:37], v[68:69], v[66:67]
	v_lshlrev_b32_e32 v68, 16, v163
	v_and_b32_e32 v69, 0xffff0000, v163
	v_mul_f32_e32 v6, 0xbfb8aa3b, v68
	v_mov_b32_e32 v22, v7
	v_mul_f32_e32 v7, 0xbfb8aa3b, v69
	v_pk_mul_f32 v[20:21], v[20:21], v[36:37]
	v_lshlrev_b32_e32 v36, 16, v109
	v_and_b32_e32 v37, 0xffff0000, v109
	v_exp_f32_e32 v6, v6
	v_exp_f32_e32 v7, v7
	v_lshlrev_b32_e32 v66, 16, v164
	v_and_b32_e32 v67, 0xffff0000, v164
	s_waitcnt vmcnt(8)
	v_pk_fma_f32 v[22:23], v[58:59], v[22:23], v[36:37] op_sel_hi:[0,1,1]
	v_pk_fma_f32 v[22:23], v[148:149], v[66:67], v[22:23] op_sel_hi:[0,1,1]
	v_lshlrev_b32_e32 v66, 16, v106
	v_and_b32_e32 v67, 0xffff0000, v106
	v_mul_f32_e32 v39, 0xbfb8aa3b, v66
	v_mov_b32_e32 v70, v8
	v_mul_f32_e32 v8, 0xbfb8aa3b, v67
	v_add_f32_e32 v6, 1.0, v6
	v_add_f32_e32 v7, 1.0, v7
	v_exp_f32_e32 v39, v39
	v_exp_f32_e32 v8, v8
	v_rcp_f32_e32 v6, v6
	v_rcp_f32_e32 v7, v7
	v_add_f32_e32 v39, 1.0, v39
	v_add_f32_e32 v8, 1.0, v8
	v_mov_b32_e32 v71, v24
	v_pk_mul_f32 v[6:7], v[6:7], v[68:69]
	v_rcp_f32_e32 v68, v39
	v_rcp_f32_e32 v69, v8
	v_pk_mul_f32 v[6:7], v[22:23], v[6:7]
	v_lshlrev_b32_e32 v22, 16, v108
	v_and_b32_e32 v23, 0xffff0000, v108
	v_lshlrev_b32_e32 v36, 16, v107
	v_and_b32_e32 v37, 0xffff0000, v107
	s_waitcnt vmcnt(1)
	v_pk_fma_f32 v[22:23], v[56:57], v[70:71], v[22:23] op_sel_hi:[0,1,1]
	v_pk_fma_f32 v[22:23], v[148:149], v[36:37], v[22:23] op_sel_hi:[0,1,1]
	v_pk_mul_f32 v[36:37], v[68:69], v[66:67]
	v_lshlrev_b32_e32 v68, 16, v103
	v_and_b32_e32 v69, 0xffff0000, v103
	v_mul_f32_e32 v8, 0xbfb8aa3b, v68
	v_mov_b32_e32 v24, v9
	v_mul_f32_e32 v9, 0xbfb8aa3b, v69
	v_pk_mul_f32 v[22:23], v[22:23], v[36:37]
	v_lshlrev_b32_e32 v36, 16, v104
	v_and_b32_e32 v37, 0xffff0000, v104
	v_exp_f32_e32 v8, v8
	v_exp_f32_e32 v9, v9
	v_lshlrev_b32_e32 v66, 16, v105
	v_and_b32_e32 v67, 0xffff0000, v105
	s_waitcnt vmcnt(0)
; __device__ __forceinline__ float silu_f(float v) { return v * __builtin_amdgcn_rcpf(1.f + __expf(-v)); }
; __device__ __forceinline__ void yoff_unit(const float* d_skip, const float* gnorm, LAS unsigned char* ldsb, int unit, const bf16* XACT, const bf16* PROJ, const float* ACS, const bf16* PREVT,
;                                           const bf16* YD, bf16* MIXB, int lane, int wave) {
;     ...
;             for (int i = 0; i < 16; ++i) {
;                 const float y0 = (__uint_as_float(yo[i] << 16) + eav[i] * Y0[i] + dsk * __uint_as_float(xsv[i] << 16)) * silu_f(__uint_as_float(zv[i] << 16));
;                 const float y1 = (__uint_as_float(yo[i] & 0xffff0000u) + eav[i] * Y1[i] + dsk * __uint_as_float(xsv[i] & 0xffff0000u)) * silu_f(__uint_as_float(zv[i] & 0xffff0000u));
;                 ssq[i] += y0 * y0 + y1 * y1; ypk[hsel][i] = pkbf(y0, y1);
	v_pk_fma_f32 v[24:25], v[54:55], v[24:25], v[36:37] op_sel_hi:[0,1,1]
	v_pk_fma_f32 v[24:25], v[148:149], v[66:67], v[24:25] op_sel_hi:[0,1,1]
	v_lshlrev_b32_e32 v66, 16, v102
	v_and_b32_e32 v67, 0xffff0000, v102
	v_mul_f32_e32 v39, 0xbfb8aa3b, v66
	v_mov_b32_e32 v70, v10
	v_mul_f32_e32 v10, 0xbfb8aa3b, v67
	v_add_f32_e32 v8, 1.0, v8
	v_add_f32_e32 v9, 1.0, v9
	v_exp_f32_e32 v39, v39
	v_exp_f32_e32 v10, v10
	v_rcp_f32_e32 v8, v8
	v_rcp_f32_e32 v9, v9
	v_add_f32_e32 v39, 1.0, v39
	v_add_f32_e32 v10, 1.0, v10
	v_mov_b32_e32 v71, v26
	v_pk_mul_f32 v[8:9], v[8:9], v[68:69]
	v_rcp_f32_e32 v68, v39
	v_rcp_f32_e32 v69, v10
	v_pk_mul_f32 v[8:9], v[24:25], v[8:9]
	v_lshlrev_b32_e32 v24, 16, v100
	v_and_b32_e32 v25, 0xffff0000, v100
	v_lshlrev_b32_e32 v36, 16, v101
	v_and_b32_e32 v37, 0xffff0000, v101
	v_pk_fma_f32 v[24:25], v[52:53], v[70:71], v[24:25] op_sel_hi:[0,1,1]
	v_pk_fma_f32 v[24:25], v[148:149], v[36:37], v[24:25] op_sel_hi:[0,1,1]
	v_pk_mul_f32 v[36:37], v[68:69], v[66:67]
	v_lshlrev_b32_e32 v66, 16, v99
	v_and_b32_e32 v67, 0xffff0000, v99
	v_mul_f32_e32 v10, 0xbfb8aa3b, v66
	v_mov_b32_e32 v26, v11
	v_mul_f32_e32 v11, 0xbfb8aa3b, v67
	v_exp_f32_e32 v10, v10
	v_exp_f32_e32 v11, v11
	v_pk_mul_f32 v[24:25], v[24:25], v[36:37]
	v_lshlrev_b32_e32 v36, 16, v98
	v_add_f32_e32 v10, 1.0, v10
	v_add_f32_e32 v11, 1.0, v11
	v_rcp_f32_e32 v10, v10
	v_rcp_f32_e32 v11, v11
	v_and_b32_e32 v37, 0xffff0000, v98
	v_pk_fma_f32 v[26:27], v[50:51], v[26:27], v[36:37] op_sel_hi:[0,1,1]
	v_lshlrev_b32_e32 v50, 16, v89
	v_and_b32_e32 v51, 0xffff0000, v89
	v_pk_mul_f32 v[10:11], v[10:11], v[66:67]
	v_mul_f32_e32 v39, 0xbfb8aa3b, v50
	v_mov_b32_e32 v66, v12
	v_mul_f32_e32 v12, 0xbfb8aa3b, v51
	v_exp_f32_e32 v39, v39
	v_exp_f32_e32 v12, v12
	v_lshlrev_b32_e32 v52, 16, v93
	v_and_b32_e32 v53, 0xffff0000, v93
	v_add_f32_e32 v39, 1.0, v39
	v_add_f32_e32 v12, 1.0, v12
	v_pk_fma_f32 v[26:27], v[148:149], v[52:53], v[26:27] op_sel_hi:[0,1,1]
	v_rcp_f32_e32 v52, v39
	v_rcp_f32_e32 v53, v12
	v_pk_mul_f32 v[10:11], v[26:27], v[10:11]
	v_lshlrev_b32_e32 v26, 16, v96
	v_and_b32_e32 v27, 0xffff0000, v96
	v_mov_b32_e32 v67, v28
	v_lshlrev_b32_e32 v36, 16, v97
	v_and_b32_e32 v37, 0xffff0000, v97
	v_pk_fma_f32 v[26:27], v[48:49], v[66:67], v[26:27] op_sel_hi:[0,1,1]
	v_pk_fma_f32 v[26:27], v[148:149], v[36:37], v[26:27] op_sel_hi:[0,1,1]
	v_pk_mul_f32 v[36:37], v[52:53], v[50:51]
	v_lshlrev_b32_e32 v50, 16, v88
	v_and_b32_e32 v51, 0xffff0000, v88
	v_mul_f32_e32 v12, 0xbfb8aa3b, v50
	v_mov_b32_e32 v28, v13
	v_mul_f32_e32 v13, 0xbfb8aa3b, v51
	v_exp_f32_e32 v12, v12
	v_exp_f32_e32 v13, v13
	v_pk_mul_f32 v[26:27], v[26:27], v[36:37]
	v_lshlrev_b32_e32 v36, 16, v95
	v_add_f32_e32 v12, 1.0, v12
	v_add_f32_e32 v13, 1.0, v13
	v_rcp_f32_e32 v12, v12
	v_rcp_f32_e32 v13, v13
	v_and_b32_e32 v37, 0xffff0000, v95
	v_pk_fma_f32 v[28:29], v[46:47], v[28:29], v[36:37] op_sel_hi:[0,1,1]
	v_lshlrev_b32_e32 v46, 16, v87
	v_and_b32_e32 v47, 0xffff0000, v87
	v_pk_mul_f32 v[12:13], v[12:13], v[50:51]
	v_mul_f32_e32 v39, 0xbfb8aa3b, v46
	v_mov_b32_e32 v50, v14
	v_mul_f32_e32 v14, 0xbfb8aa3b, v47
	v_exp_f32_e32 v39, v39
	v_exp_f32_e32 v14, v14
	v_lshlrev_b32_e32 v48, 16, v92
	v_and_b32_e32 v49, 0xffff0000, v92
	v_add_f32_e32 v39, 1.0, v39
	v_add_f32_e32 v14, 1.0, v14
	v_pk_fma_f32 v[28:29], v[148:149], v[48:49], v[28:29] op_sel_hi:[0,1,1]
	v_rcp_f32_e32 v48, v39
	v_rcp_f32_e32 v49, v14
	v_pk_mul_f32 v[12:13], v[28:29], v[12:13]
	v_lshlrev_b32_e32 v28, 16, v94
	v_and_b32_e32 v29, 0xffff0000, v94
	v_mov_b32_e32 v51, v30
	v_lshlrev_b32_e32 v36, 16, v91
	v_and_b32_e32 v37, 0xffff0000, v91
	v_pk_fma_f32 v[28:29], v[44:45], v[50:51], v[28:29] op_sel_hi:[0,1,1]
	v_pk_fma_f32 v[28:29], v[148:149], v[36:37], v[28:29] op_sel_hi:[0,1,1]
	v_pk_mul_f32 v[36:37], v[48:49], v[46:47]
	v_lshlrev_b32_e32 v46, 16, v86
	v_and_b32_e32 v47, 0xffff0000, v86
	v_mul_f32_e32 v14, 0xbfb8aa3b, v46
	v_mov_b32_e32 v30, v15
	v_mul_f32_e32 v15, 0xbfb8aa3b, v47
	v_exp_f32_e32 v14, v14
	v_exp_f32_e32 v15, v15
	v_pk_mul_f32 v[28:29], v[28:29], v[36:37]
	v_lshlrev_b32_e32 v36, 16, v65
	v_add_f32_e32 v14, 1.0, v14
	v_add_f32_e32 v15, 1.0, v15
	v_rcp_f32_e32 v14, v14
	v_rcp_f32_e32 v15, v15
	v_and_b32_e32 v37, 0xffff0000, v65
	v_pk_fma_f32 v[30:31], v[42:43], v[30:31], v[36:37] op_sel_hi:[0,1,1]
	v_lshlrev_b32_e32 v42, 16, v57
	v_and_b32_e32 v43, 0xffff0000, v57
	v_pk_mul_f32 v[14:15], v[14:15], v[46:47]
	v_mul_f32_e32 v39, 0xbfb8aa3b, v42
	v_mov_b32_e32 v46, v16
	v_mul_f32_e32 v16, 0xbfb8aa3b, v43
	v_exp_f32_e32 v39, v39
	v_exp_f32_e32 v16, v16
	v_lshlrev_b32_e32 v44, 16, v90
	v_and_b32_e32 v45, 0xffff0000, v90
	v_add_f32_e32 v39, 1.0, v39
	v_add_f32_e32 v16, 1.0, v16
	v_pk_fma_f32 v[30:31], v[148:149], v[44:45], v[30:31] op_sel_hi:[0,1,1]
	v_rcp_f32_e32 v44, v39
	v_rcp_f32_e32 v45, v16
	v_pk_mul_f32 v[14:15], v[30:31], v[14:15]
	v_lshlrev_b32_e32 v30, 16, v64
	v_and_b32_e32 v31, 0xffff0000, v64
	v_mov_b32_e32 v47, v32
	v_lshlrev_b32_e32 v36, 16, v61
	v_and_b32_e32 v37, 0xffff0000, v61
	v_pk_fma_f32 v[30:31], v[40:41], v[46:47], v[30:31] op_sel_hi:[0,1,1]
	v_pk_fma_f32 v[30:31], v[148:149], v[36:37], v[30:31] op_sel_hi:[0,1,1]
	v_pk_mul_f32 v[36:37], v[44:45], v[42:43]
	v_lshlrev_b32_e32 v42, 16, v55
	v_and_b32_e32 v43, 0xffff0000, v55
	v_mul_f32_e32 v16, 0xbfb8aa3b, v42
	v_mov_b32_e32 v32, v17
	v_mul_f32_e32 v17, 0xbfb8aa3b, v43
	v_exp_f32_e32 v16, v16
	v_exp_f32_e32 v17, v17
	v_pk_mul_f32 v[30:31], v[30:31], v[36:37]
	v_lshlrev_b32_e32 v36, 16, v63
	v_add_f32_e32 v16, 1.0, v16
	v_add_f32_e32 v17, 1.0, v17
	v_rcp_f32_e32 v16, v16
	v_rcp_f32_e32 v17, v17
	v_and_b32_e32 v37, 0xffff0000, v63
	v_lshlrev_b32_e32 v40, 16, v59
; __device__ __forceinline__ void yoff_unit(const float* d_skip, const float* gnorm, LAS unsigned char* ldsb, int unit, const bf16* XACT, const bf16* PROJ, const float* ACS, const bf16* PREVT,
;                                           const bf16* YD, bf16* MIXB, int lane, int wave) {
;     ...
;                 ssq[i] += y0 * y0 + y1 * y1; ypk[hsel][i] = pkbf(y0, y1);
;             }
;         }
;     }
; #pragma unroll
;     for (int i = 0; i < 16; ++i) {
; #pragma unroll
;         for (int o = 1; o < 32; o <<= 1) ssq[i] += __shfl_xor(ssq[i], o);
;     }
;     ...
;         const unsigned col = (unsigned)((g * 4 + 2 * hpair + hsel) * 64 + 2 * r); const float gn0 = gnorm[col], gn1 = gnorm[col + 1];
	v_and_b32_e32 v41, 0xffff0000, v59
	v_pk_fma_f32 v[32:33], v[38:39], v[32:33], v[36:37] op_sel_hi:[0,1,1]
	v_pk_fma_f32 v[32:33], v[148:149], v[40:41], v[32:33] op_sel_hi:[0,1,1]
	v_pk_mul_f32 v[16:17], v[16:17], v[42:43]
	v_cmp_lt_i32_e64 s[4:5], v157, v156
	v_pk_mul_f32 v[16:17], v[32:33], v[16:17]
	v_mov_b32_e32 v36, v117
	v_cndmask_b32_e64 v32, v155, v157, s[4:5]
	v_cmp_lt_i32_e64 s[4:5], v158, v156
	v_lshlrev_b32_e32 v66, 2, v32
	v_mov_b32_e32 v37, v119
	v_cndmask_b32_e64 v32, v155, v158, s[4:5]
	v_cmp_lt_i32_e64 s[4:5], v159, v156
	v_lshlrev_b32_e32 v64, 2, v32
	v_mov_b32_e32 v33, v118
	v_cndmask_b32_e64 v32, v155, v159, s[4:5]
	v_cmp_lt_i32_e64 s[4:5], v160, v156
	v_lshlrev_b32_e32 v63, 2, v32
	v_pk_mul_f32 v[36:37], v[36:37], v[36:37]
	v_cndmask_b32_e64 v32, v155, v160, s[4:5]
	v_cmp_lt_i32_e64 s[4:5], v161, v156
	v_lshlrev_b32_e32 v62, 2, v32
	v_mov_b32_e32 v38, v35
	v_cndmask_b32_e64 v32, v155, v161, s[4:5]
	v_lshlrev_b32_e32 v65, 2, v32
	v_mov_b32_e32 v32, v116
	v_mov_b32_e32 v39, v3
	v_pk_fma_f32 v[32:33], v[32:33], v[32:33], v[36:37]
	v_mov_b32_e32 v36, v34
	v_mov_b32_e32 v37, v2
	v_pk_mul_f32 v[38:39], v[38:39], v[38:39]
	v_mov_b32_e32 v40, v121
	v_mov_b32_e32 v41, v123
	v_pk_fma_f32 v[36:37], v[36:37], v[36:37], v[38:39]
	v_mov_b32_e32 v38, v120
	v_mov_b32_e32 v39, v122
	v_pk_mul_f32 v[40:41], v[40:41], v[40:41]
	v_mov_b32_e32 v42, v19
	v_mov_b32_e32 v43, v5
	v_pk_fma_f32 v[38:39], v[38:39], v[38:39], v[40:41]
	v_mov_b32_e32 v40, v18
	v_mov_b32_e32 v41, v4
	v_pk_mul_f32 v[42:43], v[42:43], v[42:43]
	v_mov_b32_e32 v44, v125
	v_mov_b32_e32 v45, v127
	v_pk_fma_f32 v[40:41], v[40:41], v[40:41], v[42:43]
	v_mov_b32_e32 v42, v124
	v_mov_b32_e32 v43, v126
	v_pk_mul_f32 v[44:45], v[44:45], v[44:45]
	v_mov_b32_e32 v46, v21
	v_mov_b32_e32 v47, v7
	v_pk_fma_f32 v[42:43], v[42:43], v[42:43], v[44:45]
	v_mov_b32_e32 v44, v20
	v_mov_b32_e32 v45, v6
	v_pk_mul_f32 v[46:47], v[46:47], v[46:47]
	v_mov_b32_e32 v48, v129
	v_mov_b32_e32 v49, v131
	v_pk_fma_f32 v[44:45], v[44:45], v[44:45], v[46:47]
	v_mov_b32_e32 v46, v128
	v_mov_b32_e32 v47, v130
	v_pk_mul_f32 v[48:49], v[48:49], v[48:49]
	v_mov_b32_e32 v50, v23
	v_mov_b32_e32 v51, v9
	v_pk_fma_f32 v[46:47], v[46:47], v[46:47], v[48:49]
	v_mov_b32_e32 v48, v22
	v_mov_b32_e32 v49, v8
	v_pk_mul_f32 v[50:51], v[50:51], v[50:51]
	v_mov_b32_e32 v52, v133
	v_mov_b32_e32 v53, v135
	v_pk_fma_f32 v[48:49], v[48:49], v[48:49], v[50:51]
	v_mov_b32_e32 v50, v132
	v_mov_b32_e32 v51, v134
	v_pk_mul_f32 v[52:53], v[52:53], v[52:53]
	v_mov_b32_e32 v54, v25
	v_mov_b32_e32 v55, v11
	v_pk_fma_f32 v[50:51], v[50:51], v[50:51], v[52:53]
	v_mov_b32_e32 v52, v24
	v_mov_b32_e32 v53, v10
	v_pk_mul_f32 v[54:55], v[54:55], v[54:55]
	v_mov_b32_e32 v56, v137
	v_mov_b32_e32 v57, v139
	v_pk_fma_f32 v[52:53], v[52:53], v[52:53], v[54:55]
	v_mov_b32_e32 v54, v136
	v_mov_b32_e32 v55, v138
	v_pk_mul_f32 v[56:57], v[56:57], v[56:57]
	v_mov_b32_e32 v58, v27
	v_mov_b32_e32 v59, v13
	v_pk_fma_f32 v[54:55], v[54:55], v[54:55], v[56:57]
	v_mov_b32_e32 v56, v26
	v_mov_b32_e32 v57, v12
	v_pk_mul_f32 v[58:59], v[58:59], v[58:59]
	v_mov_b32_e32 v60, v141
	v_mov_b32_e32 v61, v143
	v_pk_fma_f32 v[56:57], v[56:57], v[56:57], v[58:59]
	v_mov_b32_e32 v58, v140
	v_mov_b32_e32 v59, v142
	v_pk_mul_f32 v[60:61], v[60:61], v[60:61]
	v_mov_b32_e32 v68, v29
	v_mov_b32_e32 v69, v15
	v_pk_fma_f32 v[58:59], v[58:59], v[58:59], v[60:61]
	v_mov_b32_e32 v60, v28
	v_mov_b32_e32 v61, v14
	v_pk_mul_f32 v[68:69], v[68:69], v[68:69]
	v_mov_b32_e32 v70, v145
	v_mov_b32_e32 v71, v147
	v_pk_fma_f32 v[60:61], v[60:61], v[60:61], v[68:69]
	v_mov_b32_e32 v68, v144
	v_mov_b32_e32 v69, v146
	v_pk_mul_f32 v[70:71], v[70:71], v[70:71]
	v_mov_b32_e32 v72, v31
	v_mov_b32_e32 v73, v17
	v_pk_fma_f32 v[68:69], v[68:69], v[68:69], v[70:71]
	v_mov_b32_e32 v70, v30
	v_mov_b32_e32 v71, v16
	v_pk_mul_f32 v[72:73], v[72:73], v[72:73]
	v_pk_add_f32 v[32:33], v[32:33], v[36:37]
	v_pk_fma_f32 v[70:71], v[70:71], v[70:71], v[72:73]
	v_pk_add_f32 v[38:39], v[38:39], v[40:41]
	v_pk_add_f32 v[42:43], v[42:43], v[44:45]
	v_pk_add_f32 v[46:47], v[46:47], v[48:49]
	v_pk_add_f32 v[50:51], v[50:51], v[52:53]
	v_pk_add_f32 v[54:55], v[54:55], v[56:57]
	v_pk_add_f32 v[58:59], v[58:59], v[60:61]
	v_pk_add_f32 v[68:69], v[68:69], v[70:71]
	v_readlane_b32 s98, v235, 20
	v_readlane_b32 s99, v235, 21
	v_mov_b32_e32 v84, v114
	v_mov_b32_e32 v85, v111
	s_nop 1
	s_nop 0
	v_lshl_add_u64 v[86:87], v[84:85], 2, s[98:99]
	global_load_dwordx2 v[88:89], v[86:87], off
	v_lshl_add_u64 v[86:87], v[110:111], 2, s[98:99]
	global_load_dwordx2 v[90:91], v[86:87], off
	ds_bpermute_b32 v36, v66, v32
	ds_bpermute_b32 v37, v66, v33
	ds_bpermute_b32 v40, v66, v38
	ds_bpermute_b32 v41, v66, v39
	ds_bpermute_b32 v44, v66, v42
	ds_bpermute_b32 v45, v66, v43
	ds_bpermute_b32 v48, v66, v46
	ds_bpermute_b32 v49, v66, v47
	ds_bpermute_b32 v52, v66, v50
	ds_bpermute_b32 v53, v66, v51
	ds_bpermute_b32 v56, v66, v54
	ds_bpermute_b32 v57, v66, v55
	ds_bpermute_b32 v60, v66, v58
	ds_bpermute_b32 v61, v66, v59
	ds_bpermute_b32 v70, v66, v68
	ds_bpermute_b32 v71, v66, v69
	s_waitcnt lgkmcnt(14)
	v_pk_add_f32 v[32:33], v[32:33], v[36:37]
	s_waitcnt lgkmcnt(12)
	v_pk_add_f32 v[38:39], v[38:39], v[40:41]
	s_waitcnt lgkmcnt(10)
	v_pk_add_f32 v[42:43], v[42:43], v[44:45]
	s_waitcnt lgkmcnt(8)
	v_pk_add_f32 v[46:47], v[46:47], v[48:49]
	s_waitcnt lgkmcnt(6)
	v_pk_add_f32 v[50:51], v[50:51], v[52:53]
	s_waitcnt lgkmcnt(4)
	v_pk_add_f32 v[54:55], v[54:55], v[56:57]
	s_waitcnt lgkmcnt(2)
	v_pk_add_f32 v[58:59], v[58:59], v[60:61]
	s_waitcnt lgkmcnt(0)
; __device__ __forceinline__ int crow(int i, int hi) { return (i & 3) + 8 * (i >> 2) + 4 * hi; }
; __device__ __forceinline__ void yoff_unit(const float* d_skip, const float* gnorm, LAS unsigned char* ldsb, int unit, const bf16* XACT, const bf16* PROJ, const float* ACS, const bf16* PREVT,
;                                           const bf16* YD, bf16* MIXB, int lane, int wave) {
;     ...
; #pragma unroll
;     for (int i = 0; i < 16; ++i) {
; #pragma unroll
;         for (int o = 1; o < 32; o <<= 1) ssq[i] += __shfl_xor(ssq[i], o);
;     }
;     if (r == 0) {
; #pragma unroll
;         for (int i = 0; i < 16; ++i) TAB[hpair * 128 + 32 * lt + crow(i, hi)] = ssq[i];
;     }
	v_pk_add_f32 v[66:67], v[68:69], v[70:71]
	ds_bpermute_b32 v36, v64, v32
	ds_bpermute_b32 v37, v64, v33
	ds_bpermute_b32 v40, v64, v38
	ds_bpermute_b32 v41, v64, v39
	ds_bpermute_b32 v44, v64, v42
	ds_bpermute_b32 v45, v64, v43
	ds_bpermute_b32 v48, v64, v46
	ds_bpermute_b32 v49, v64, v47
	ds_bpermute_b32 v52, v64, v50
	ds_bpermute_b32 v53, v64, v51
	ds_bpermute_b32 v56, v64, v54
	ds_bpermute_b32 v57, v64, v55
	ds_bpermute_b32 v60, v64, v58
	ds_bpermute_b32 v61, v64, v59
	ds_bpermute_b32 v68, v64, v66
	ds_bpermute_b32 v69, v64, v67
	s_waitcnt lgkmcnt(14)
	v_pk_add_f32 v[32:33], v[32:33], v[36:37]
	s_waitcnt lgkmcnt(12)
	v_pk_add_f32 v[38:39], v[38:39], v[40:41]
	s_waitcnt lgkmcnt(10)
	v_pk_add_f32 v[42:43], v[42:43], v[44:45]
	s_waitcnt lgkmcnt(8)
	v_pk_add_f32 v[46:47], v[46:47], v[48:49]
	s_waitcnt lgkmcnt(6)
	v_pk_add_f32 v[50:51], v[50:51], v[52:53]
	s_waitcnt lgkmcnt(4)
	v_pk_add_f32 v[54:55], v[54:55], v[56:57]
	s_waitcnt lgkmcnt(2)
	v_pk_add_f32 v[58:59], v[58:59], v[60:61]
	s_waitcnt lgkmcnt(0)
	v_pk_add_f32 v[66:67], v[66:67], v[68:69]
	ds_bpermute_b32 v36, v63, v32
	ds_bpermute_b32 v37, v63, v33
	ds_bpermute_b32 v40, v63, v38
	ds_bpermute_b32 v41, v63, v39
	ds_bpermute_b32 v44, v63, v42
	ds_bpermute_b32 v45, v63, v43
	ds_bpermute_b32 v48, v63, v46
	ds_bpermute_b32 v49, v63, v47
	ds_bpermute_b32 v52, v63, v50
	ds_bpermute_b32 v53, v63, v51
	ds_bpermute_b32 v56, v63, v54
	ds_bpermute_b32 v57, v63, v55
	ds_bpermute_b32 v60, v63, v58
	ds_bpermute_b32 v61, v63, v59
	ds_bpermute_b32 v68, v63, v66
	ds_bpermute_b32 v69, v63, v67
	s_waitcnt lgkmcnt(14)
	v_pk_add_f32 v[32:33], v[32:33], v[36:37]
	s_waitcnt lgkmcnt(12)
	v_pk_add_f32 v[38:39], v[38:39], v[40:41]
	s_waitcnt lgkmcnt(10)
	v_pk_add_f32 v[42:43], v[42:43], v[44:45]
	s_waitcnt lgkmcnt(8)
	v_pk_add_f32 v[46:47], v[46:47], v[48:49]
	s_waitcnt lgkmcnt(6)
	v_pk_add_f32 v[50:51], v[50:51], v[52:53]
	s_waitcnt lgkmcnt(4)
	v_pk_add_f32 v[54:55], v[54:55], v[56:57]
	s_waitcnt lgkmcnt(2)
	v_pk_add_f32 v[58:59], v[58:59], v[60:61]
	s_waitcnt lgkmcnt(0)
	v_pk_add_f32 v[66:67], v[66:67], v[68:69]
	ds_bpermute_b32 v36, v62, v32
	ds_bpermute_b32 v37, v62, v33
	ds_bpermute_b32 v40, v62, v38
	ds_bpermute_b32 v41, v62, v39
	ds_bpermute_b32 v44, v62, v42
	ds_bpermute_b32 v45, v62, v43
	ds_bpermute_b32 v48, v62, v46
	ds_bpermute_b32 v49, v62, v47
	ds_bpermute_b32 v52, v62, v50
	ds_bpermute_b32 v53, v62, v51
	ds_bpermute_b32 v56, v62, v54
	ds_bpermute_b32 v57, v62, v55
	ds_bpermute_b32 v60, v62, v58
	ds_bpermute_b32 v61, v62, v59
	ds_bpermute_b32 v68, v62, v66
	ds_bpermute_b32 v69, v62, v67
	s_waitcnt lgkmcnt(14)
	v_pk_add_f32 v[32:33], v[32:33], v[36:37]
	s_waitcnt lgkmcnt(12)
	v_pk_add_f32 v[38:39], v[38:39], v[40:41]
	s_waitcnt lgkmcnt(10)
	v_pk_add_f32 v[42:43], v[42:43], v[44:45]
	s_waitcnt lgkmcnt(8)
	v_pk_add_f32 v[46:47], v[46:47], v[48:49]
	s_waitcnt lgkmcnt(6)
	v_pk_add_f32 v[50:51], v[50:51], v[52:53]
	s_waitcnt lgkmcnt(4)
	v_pk_add_f32 v[54:55], v[54:55], v[56:57]
	s_waitcnt lgkmcnt(2)
	v_pk_add_f32 v[58:59], v[58:59], v[60:61]
	s_waitcnt lgkmcnt(0)
	v_pk_add_f32 v[62:63], v[66:67], v[68:69]
	ds_bpermute_b32 v36, v65, v32
	ds_bpermute_b32 v37, v65, v33
	ds_bpermute_b32 v40, v65, v38
	ds_bpermute_b32 v41, v65, v39
	ds_bpermute_b32 v44, v65, v42
	ds_bpermute_b32 v45, v65, v43
	ds_bpermute_b32 v48, v65, v46
	ds_bpermute_b32 v49, v65, v47
	ds_bpermute_b32 v52, v65, v50
	ds_bpermute_b32 v53, v65, v51
	ds_bpermute_b32 v56, v65, v54
	ds_bpermute_b32 v57, v65, v55
	ds_bpermute_b32 v60, v65, v58
	ds_bpermute_b32 v61, v65, v59
	ds_bpermute_b32 v64, v65, v62
	ds_bpermute_b32 v65, v65, v63
	s_and_saveexec_b64 s[4:5], vcc
	s_cbranch_execz .LBB0_468
	s_waitcnt lgkmcnt(14)
	v_pk_add_f32 v[36:37], v[32:33], v[36:37]
	s_waitcnt lgkmcnt(12)
	v_pk_add_f32 v[38:39], v[38:39], v[40:41]
	ds_write_b128 v153, v[36:39]
	s_waitcnt lgkmcnt(11)
	v_pk_add_f32 v[36:37], v[42:43], v[44:45]
	s_waitcnt lgkmcnt(9)
	v_pk_add_f32 v[38:39], v[46:47], v[48:49]
	ds_write_b128 v153, v[36:39] offset:32
	s_waitcnt lgkmcnt(8)
	v_pk_add_f32 v[36:37], v[50:51], v[52:53]
	s_waitcnt lgkmcnt(6)
	v_pk_add_f32 v[38:39], v[54:55], v[56:57]
	ds_write_b128 v153, v[36:39] offset:64
	s_waitcnt lgkmcnt(5)
	v_pk_add_f32 v[36:37], v[58:59], v[60:61]
	s_waitcnt lgkmcnt(3)
	v_pk_add_f32 v[38:39], v[62:63], v[64:65]
	ds_write_b128 v153, v[36:39] offset:96
; __device__ __forceinline__ int crow(int i, int hi) { return (i & 3) + 8 * (i >> 2) + 4 * hi; }
; __device__ __forceinline__ void yoff_unit(const float* d_skip, const float* gnorm, LAS unsigned char* ldsb, int unit, const bf16* XACT, const bf16* PROJ, const float* ACS, const bf16* PREVT,
;                                           const bf16* YD, bf16* MIXB, int lane, int wave) {
;     ...
;     __syncthreads();
; #pragma unroll
;     for (int i = 0; i < 16; ++i) { const int l = 32 * lt + crow(i, hi); ssq[i] = rsqrtf((TAB[l] + TAB[128 + l]) * (1.f / 256.f) + EPS); }
; #pragma unroll
;     for (int hsel = 0; hsel < 2; ++hsel) {
;         const unsigned col = (unsigned)((g * 4 + 2 * hpair + hsel) * 64 + 2 * r); const float gn0 = gnorm[col], gn1 = gnorm[col + 1];
;         const unsigned voB = (tb * 1024u + 512u + col) * 2u;
.LBB0_468:
	s_or_b64 exec, exec, s[4:5]
	v_cvt_pk_bf16_f32 v38, v4, v5
	v_cvt_pk_bf16_f32 v39, v2, v3
	s_waitcnt lgkmcnt(0)
	s_barrier
	ds_read_b128 v[56:59], v154
	ds_read_b128 v[2:5], v154 offset:32
	ds_read_b128 v[60:63], v154 offset:512
	s_mov_b32 s4, 0x358637bd
	v_cvt_pk_bf16_f32 v33, v20, v21
	v_mov_b64_e32 v[20:21], s[4:5]
	v_cvt_pk_bf16_f32 v7, v6, v7
	s_waitcnt lgkmcnt(0)
	v_pk_add_f32 v[36:37], v[56:57], v[60:61]
	v_cvt_pk_bf16_f32 v9, v8, v9
	v_pk_fma_f32 v[36:37], v[36:37], s[22:23], v[20:21] op_sel_hi:[1,0,0]
	v_cvt_pk_bf16_f32 v13, v12, v13
	v_mul_f32_e32 v6, 0x4b800000, v36
	v_cmp_gt_f32_e64 s[6:7], s92, v36
	v_cmp_gt_f32_e64 s[4:5], s92, v37
	v_cvt_pk_bf16_f32 v11, v10, v11
	v_cndmask_b32_e64 v6, v36, v6, s[6:7]
	v_rsq_f32_e32 v6, v6
	v_cvt_pk_bf16_f32 v15, v14, v15
	v_cvt_pk_bf16_f32 v31, v30, v31
	v_cvt_pk_bf16_f32 v23, v22, v23
	v_mul_f32_e32 v8, 0x45800000, v6
	v_cndmask_b32_e64 v12, v6, v8, s[6:7]
	v_mul_f32_e32 v6, 0x4b800000, v37
	v_cndmask_b32_e64 v6, v37, v6, s[4:5]
	v_rsq_f32_e32 v6, v6
	v_pk_add_f32 v[36:37], v[58:59], v[62:63]
	ds_read_b128 v[56:59], v154 offset:544
	v_pk_fma_f32 v[36:37], v[36:37], s[22:23], v[20:21] op_sel_hi:[1,0,0]
	v_mul_f32_e32 v8, 0x45800000, v6
	v_cndmask_b32_e64 v8, v6, v8, s[4:5]
	v_mul_f32_e32 v6, 0x4b800000, v36
	v_cmp_gt_f32_e64 s[6:7], s92, v36
	v_cmp_gt_f32_e64 s[4:5], s92, v37
	s_waitcnt lgkmcnt(0)
	v_pk_add_f32 v[2:3], v[2:3], v[56:57]
	v_cndmask_b32_e64 v6, v36, v6, s[6:7]
	v_rsq_f32_e32 v6, v6
	v_pk_fma_f32 v[2:3], v[2:3], s[22:23], v[20:21] op_sel_hi:[1,0,0]
	v_pk_add_f32 v[4:5], v[4:5], v[58:59]
	ds_read_b128 v[56:59], v154 offset:64
	ds_read_b128 v[60:63], v154 offset:576
	v_mul_f32_e32 v10, 0x45800000, v6
	v_cndmask_b32_e64 v10, v6, v10, s[6:7]
	v_mul_f32_e32 v6, 0x4b800000, v37
	v_cndmask_b32_e64 v6, v37, v6, s[4:5]
	v_rsq_f32_e32 v6, v6
	v_cmp_gt_f32_e64 s[6:7], s92, v2
	v_pk_fma_f32 v[4:5], v[4:5], s[22:23], v[20:21] op_sel_hi:[1,0,0]
	v_cvt_pk_bf16_f32 v25, v24, v25
	v_mul_f32_e32 v14, 0x45800000, v6
	v_cndmask_b32_e64 v6, v6, v14, s[4:5]
	v_mul_f32_e32 v14, 0x4b800000, v2
	v_cndmask_b32_e64 v2, v2, v14, s[6:7]
	v_rsq_f32_e32 v2, v2
	v_cmp_gt_f32_e64 s[4:5], s92, v3
	v_cvt_pk_bf16_f32 v27, v26, v27
	v_cvt_pk_bf16_f32 v17, v16, v17
	v_mul_f32_e32 v14, 0x45800000, v2
	v_cndmask_b32_e64 v2, v2, v14, s[6:7]
	v_mul_f32_e32 v14, 0x4b800000, v3
	v_cndmask_b32_e64 v3, v3, v14, s[4:5]
	v_rsq_f32_e32 v3, v3
	v_cmp_gt_f32_e64 s[6:7], s92, v4
	v_cvt_pk_bf16_f32 v29, v28, v29
	v_cvt_pk_bf16_f32 v19, v18, v19
	v_mul_f32_e32 v14, 0x45800000, v3
	v_cndmask_b32_e64 v14, v3, v14, s[4:5]
	v_mul_f32_e32 v3, 0x4b800000, v4
	v_cndmask_b32_e64 v3, v4, v3, s[6:7]
	v_rsq_f32_e32 v3, v3
	v_cmp_gt_f32_e64 s[4:5], s92, v5
	v_readlane_b32 s64, v235, 16
	v_readlane_b32 s68, v235, 20
	v_mul_f32_e32 v4, 0x45800000, v3
	v_cndmask_b32_e64 v30, v3, v4, s[6:7]
	v_mul_f32_e32 v3, 0x4b800000, v5
	v_cndmask_b32_e64 v3, v5, v3, s[4:5]
	v_rsq_f32_e32 v3, v3
	v_readlane_b32 s69, v235, 21
	v_cvt_pk_bf16_f32 v40, v34, v35
	v_cvt_pk_bf16_f32 v34, v116, v117
	v_mul_f32_e32 v4, 0x45800000, v3
	v_cndmask_b32_e64 v22, v3, v4, s[4:5]
	s_waitcnt lgkmcnt(0)
	v_pk_add_f32 v[4:5], v[56:57], v[60:61]
	v_lshlrev_b32_e32 v36, 16, v34
	v_pk_fma_f32 v[4:5], v[4:5], s[22:23], v[20:21] op_sel_hi:[1,0,0]
	v_and_b32_e32 v37, 0xffff0000, v34
	v_mul_f32_e32 v3, 0x4b800000, v4
	v_cmp_gt_f32_e64 s[6:7], s92, v4
	v_cmp_gt_f32_e64 s[4:5], s92, v5
	v_pk_mul_f32 v[36:37], v[12:13], v[36:37] op_sel_hi:[0,1]
	v_cndmask_b32_e64 v3, v4, v3, s[6:7]
	v_rsq_f32_e32 v3, v3
	v_cvt_pk_bf16_f32 v55, v118, v119
	v_cvt_pk_bf16_f32 v54, v120, v121
	v_cvt_pk_bf16_f32 v53, v122, v123
	v_mul_f32_e32 v4, 0x45800000, v3
	v_cndmask_b32_e64 v32, v3, v4, s[6:7]
	v_mul_f32_e32 v3, 0x4b800000, v5
	v_cndmask_b32_e64 v3, v5, v3, s[4:5]
	v_rsq_f32_e32 v3, v3
	v_cvt_pk_bf16_f32 v52, v124, v125
	v_cvt_pk_bf16_f32 v51, v126, v127
	v_cvt_pk_bf16_f32 v50, v128, v129
	v_mul_f32_e32 v4, 0x45800000, v3
	v_cndmask_b32_e64 v24, v3, v4, s[4:5]
	v_pk_add_f32 v[4:5], v[58:59], v[62:63]
	ds_read_b128 v[56:59], v154 offset:96
	ds_read_b128 v[60:63], v154 offset:608
	v_pk_fma_f32 v[4:5], v[4:5], s[22:23], v[20:21] op_sel_hi:[1,0,0]
	v_cvt_pk_bf16_f32 v49, v130, v131
	v_mul_f32_e32 v3, 0x4b800000, v4
	v_cmp_gt_f32_e64 s[6:7], s92, v4
	v_cmp_gt_f32_e64 s[4:5], s92, v5
	v_cvt_pk_bf16_f32 v48, v132, v133
	v_cndmask_b32_e64 v3, v4, v3, s[6:7]
	v_rsq_f32_e32 v3, v3
	v_cvt_pk_bf16_f32 v47, v134, v135
	v_cvt_pk_bf16_f32 v46, v136, v137
	v_cvt_pk_bf16_f32 v45, v138, v139
	v_mul_f32_e32 v4, 0x45800000, v3
	v_cndmask_b32_e64 v26, v3, v4, s[6:7]
	v_mul_f32_e32 v3, 0x4b800000, v5
	v_cndmask_b32_e64 v3, v5, v3, s[4:5]
	v_rsq_f32_e32 v3, v3
	v_cvt_pk_bf16_f32 v44, v140, v141
	v_cvt_pk_bf16_f32 v43, v142, v143
	v_cvt_pk_bf16_f32 v42, v144, v145
	v_mul_f32_e32 v4, 0x45800000, v3
	v_cndmask_b32_e64 v16, v3, v4, s[4:5]
	s_waitcnt lgkmcnt(0)
	v_pk_add_f32 v[4:5], v[56:57], v[60:61]
	v_cvt_pk_bf16_f32 v41, v146, v147
	v_pk_fma_f32 v[4:5], v[4:5], s[22:23], v[20:21] op_sel_hi:[1,0,0]
	v_readlane_b32 s65, v235, 17
	v_mul_f32_e32 v3, 0x4b800000, v4
	v_cmp_gt_f32_e64 s[6:7], s92, v4
	v_cmp_gt_f32_e64 s[4:5], s92, v5
	v_readlane_b32 s66, v235, 18
	v_cndmask_b32_e64 v3, v4, v3, s[6:7]
	v_rsq_f32_e32 v3, v3
	v_readlane_b32 s67, v235, 19
	v_readlane_b32 s70, v235, 22
	v_readlane_b32 s71, v235, 23
	v_mul_f32_e32 v4, 0x45800000, v3
	v_cndmask_b32_e64 v28, v3, v4, s[6:7]
	v_mul_f32_e32 v3, 0x4b800000, v5
	v_cndmask_b32_e64 v3, v5, v3, s[4:5]
	v_rsq_f32_e32 v3, v3
	v_readlane_b32 s72, v235, 24
	v_readlane_b32 s73, v235, 25
	v_readlane_b32 s74, v235, 26
	v_mul_f32_e32 v4, 0x45800000, v3
	v_cndmask_b32_e64 v18, v3, v4, s[4:5]
	v_pk_add_f32 v[4:5], v[58:59], v[62:63]
	v_readlane_b32 s75, v235, 27
	v_pk_fma_f32 v[4:5], v[4:5], s[22:23], v[20:21] op_sel_hi:[1,0,0]
	v_readlane_b32 s76, v235, 28
	v_mul_f32_e32 v3, 0x4b800000, v4
	v_cmp_gt_f32_e64 s[6:7], s92, v4
	v_cmp_gt_f32_e64 s[4:5], s92, v5
	v_readlane_b32 s77, v235, 29
	v_cndmask_b32_e64 v3, v4, v3, s[6:7]
	v_rsq_f32_e32 v3, v3
	v_readlane_b32 s78, v235, 30
	v_readlane_b32 s79, v235, 31
	v_mul_f32_e32 v4, 0x45800000, v3
	v_cndmask_b32_e64 v20, v3, v4, s[6:7]
	v_mul_f32_e32 v3, 0x4b800000, v5
	v_cndmask_b32_e64 v3, v5, v3, s[4:5]
	v_rsq_f32_e32 v3, v3
	s_nop 0
	v_mul_f32_e32 v4, 0x45800000, v3
	v_cndmask_b32_e64 v4, v3, v4, s[4:5]
	v_or_b32_e32 v3, 0x200, v115
	v_mov_b32_e32 v115, v111
	s_waitcnt vmcnt(0)
; __device__ __forceinline__ void yoff_unit(const float* d_skip, const float* gnorm, LAS unsigned char* ldsb, int unit, const bf16* XACT, const bf16* PROJ, const float* ACS, const bf16* PREVT,
;                                           const bf16* YD, bf16* MIXB, int lane, int wave) {
;     ...
;     for (int hsel = 0; hsel < 2; ++hsel) {
;         const unsigned col = (unsigned)((g * 4 + 2 * hpair + hsel) * 64 + 2 * r); const float gn0 = gnorm[col], gn1 = gnorm[col + 1];
;         const unsigned voB = (tb * 1024u + 512u + col) * 2u;
; #pragma unroll
;         for (int i = 0; i < 16; ++i) { const unsigned w = ypk[hsel][i]; const float sn = ssq[i];
;             __builtin_amdgcn_raw_buffer_store_b32(pkbf(__uint_as_float(w << 16) * sn * gn0, __uint_as_float(w & 0xffff0000u) * sn * gn1), rsB, (int)voB, ((i & 3) + 8 * (i >> 2)) * 2048, 16); }
	v_mov_b32_e32 v34, v88
	v_mov_b32_e32 v35, v89
	s_nop 0
	v_readlane_b32 s4, v235, 44
	v_readlane_b32 s6, v235, 46
	v_readlane_b32 s7, v235, 47
	v_add_lshl_u32 v5, v3, v114, 1
	v_readlane_b32 s5, v235, 45
	s_mov_b32 s6, s10
	s_mov_b32 s7, s11
	s_mov_b64 s[24:25], s[4:5]
	v_writelane_b32 v235, s24, 44
	s_waitcnt vmcnt(0)
	v_pk_mul_f32 v[36:37], v[36:37], v[34:35]
	s_nop 0
	v_cvt_pk_bf16_f32 v21, v36, v37
	v_lshlrev_b32_e32 v36, 16, v55
	v_and_b32_e32 v37, 0xffff0000, v55
	v_pk_mul_f32 v[36:37], v[8:9], v[36:37] op_sel_hi:[0,1]
	v_pk_mul_f32 v[36:37], v[36:37], v[34:35]
	buffer_store_dword v21, v5, s[4:7], 0 offen sc1
	v_cvt_pk_bf16_f32 v21, v36, v37
	v_lshlrev_b32_e32 v36, 16, v54
	v_and_b32_e32 v37, 0xffff0000, v54
	v_pk_mul_f32 v[36:37], v[10:11], v[36:37] op_sel_hi:[0,1]
	v_pk_mul_f32 v[36:37], v[36:37], v[34:35]
	buffer_store_dword v21, v5, s[4:7], s46 offen sc1
	v_cvt_pk_bf16_f32 v21, v36, v37
	v_lshlrev_b32_e32 v36, 16, v53
	v_and_b32_e32 v37, 0xffff0000, v53
	v_pk_mul_f32 v[36:37], v[6:7], v[36:37] op_sel_hi:[0,1]
	v_pk_mul_f32 v[36:37], v[36:37], v[34:35]
	buffer_store_dword v21, v5, s[4:7], s48 offen sc1
	v_cvt_pk_bf16_f32 v21, v36, v37
	v_lshlrev_b32_e32 v36, 16, v52
	v_and_b32_e32 v37, 0xffff0000, v52
	v_pk_mul_f32 v[36:37], v[2:3], v[36:37] op_sel_hi:[0,1]
	v_pk_mul_f32 v[36:37], v[36:37], v[34:35]
	buffer_store_dword v21, v5, s[4:7], s56 offen sc1
	v_cvt_pk_bf16_f32 v21, v36, v37
	v_lshlrev_b32_e32 v36, 16, v51
	v_and_b32_e32 v37, 0xffff0000, v51
	v_pk_mul_f32 v[36:37], v[14:15], v[36:37] op_sel_hi:[0,1]
	v_pk_mul_f32 v[36:37], v[36:37], v[34:35]
	buffer_store_dword v21, v5, s[4:7], s62 offen sc1
	v_cvt_pk_bf16_f32 v21, v36, v37
	v_lshlrev_b32_e32 v36, 16, v50
	v_and_b32_e32 v37, 0xffff0000, v50
	v_pk_mul_f32 v[36:37], v[30:31], v[36:37] op_sel_hi:[0,1]
	v_pk_mul_f32 v[36:37], v[36:37], v[34:35]
	buffer_store_dword v21, v5, s[4:7], s82 offen sc1
	v_cvt_pk_bf16_f32 v21, v36, v37
	v_lshlrev_b32_e32 v36, 16, v49
	v_and_b32_e32 v37, 0xffff0000, v49
	v_pk_mul_f32 v[36:37], v[22:23], v[36:37] op_sel_hi:[0,1]
	v_pk_mul_f32 v[36:37], v[36:37], v[34:35]
	buffer_store_dword v21, v5, s[4:7], s93 offen sc1
	v_cvt_pk_bf16_f32 v21, v36, v37
	v_lshlrev_b32_e32 v36, 16, v48
	v_and_b32_e32 v37, 0xffff0000, v48
	v_pk_mul_f32 v[36:37], v[32:33], v[36:37] op_sel_hi:[0,1]
	v_pk_mul_f32 v[36:37], v[36:37], v[34:35]
	buffer_store_dword v21, v5, s[4:7], s20 offen sc1
	v_cvt_pk_bf16_f32 v21, v36, v37
	v_lshlrev_b32_e32 v36, 16, v47
	v_and_b32_e32 v37, 0xffff0000, v47
	v_pk_mul_f32 v[36:37], v[24:25], v[36:37] op_sel_hi:[0,1]
	v_pk_mul_f32 v[36:37], v[36:37], v[34:35]
	buffer_store_dword v21, v5, s[4:7], s84 offen sc1
	v_cvt_pk_bf16_f32 v21, v36, v37
	v_lshlrev_b32_e32 v36, 16, v46
	v_and_b32_e32 v37, 0xffff0000, v46
	v_pk_mul_f32 v[36:37], v[26:27], v[36:37] op_sel_hi:[0,1]
	v_pk_mul_f32 v[36:37], v[36:37], v[34:35]
	buffer_store_dword v21, v5, s[4:7], s28 offen sc1
	v_cvt_pk_bf16_f32 v21, v36, v37
	v_lshlrev_b32_e32 v36, 16, v45
	v_and_b32_e32 v37, 0xffff0000, v45
	v_pk_mul_f32 v[36:37], v[16:17], v[36:37] op_sel_hi:[0,1]
	v_pk_mul_f32 v[36:37], v[34:35], v[36:37]
	buffer_store_dword v21, v5, s[4:7], s63 offen sc1
	v_cvt_pk_bf16_f32 v21, v36, v37
	v_lshlrev_b32_e32 v36, 16, v44
	v_and_b32_e32 v37, 0xffff0000, v44
	v_pk_mul_f32 v[36:37], v[28:29], v[36:37] op_sel_hi:[0,1]
	v_pk_mul_f32 v[36:37], v[34:35], v[36:37]
	buffer_store_dword v21, v5, s[4:7], s37 offen sc1
	v_cvt_pk_bf16_f32 v21, v36, v37
	v_lshlrev_b32_e32 v36, 16, v43
	v_and_b32_e32 v37, 0xffff0000, v43
	v_pk_mul_f32 v[36:37], v[18:19], v[36:37] op_sel_hi:[0,1]
	v_pk_mul_f32 v[36:37], v[34:35], v[36:37]
	buffer_store_dword v21, v5, s[4:7], s40 offen sc1
	v_cvt_pk_bf16_f32 v21, v36, v37
	v_lshlrev_b32_e32 v36, 16, v42
	v_and_b32_e32 v37, 0xffff0000, v42
	v_pk_mul_f32 v[36:37], v[20:21], v[36:37] op_sel_hi:[0,1]
	v_pk_mul_f32 v[36:37], v[34:35], v[36:37]
	buffer_store_dword v21, v5, s[4:7], s43 offen sc1
	v_cvt_pk_bf16_f32 v21, v36, v37
	v_lshlrev_b32_e32 v36, 16, v41
	v_and_b32_e32 v37, 0xffff0000, v41
	v_pk_mul_f32 v[36:37], v[4:5], v[36:37] op_sel_hi:[0,1]
	v_pk_mul_f32 v[34:35], v[34:35], v[36:37]
	buffer_store_dword v21, v5, s[4:7], s47 offen sc1
	v_cvt_pk_bf16_f32 v21, v34, v35
	buffer_store_dword v21, v5, s[4:7], s59 offen sc1
	v_mov_b32_e32 v34, v90
	v_mov_b32_e32 v35, v91
	s_nop 0
	s_nop 0
	v_lshlrev_b32_e32 v36, 16, v40
	v_and_b32_e32 v37, 0xffff0000, v40
	v_pk_mul_f32 v[36:37], v[12:13], v[36:37] op_sel_hi:[0,1]
	v_add_lshl_u32 v5, v3, v110, 1
	v_writelane_b32 v235, s25, 45
; __device__ __forceinline__ unsigned xb_add(unsigned* p, unsigned v) { return __hip_atomic_fetch_add(p, v, __ATOMIC_RELAXED, __HIP_MEMORY_SCOPE_AGENT); }
; __device__ __forceinline__ void yoff_unit(const float* d_skip, const float* gnorm, LAS unsigned char* ldsb, int unit, const bf16* XACT, const bf16* PROJ, const float* ACS, const bf16* PREVT,
;                                           const bf16* YD, bf16* MIXB, int lane, int wave) {
;     ...
;     for (int hsel = 0; hsel < 2; ++hsel) {
;         const unsigned col = (unsigned)((g * 4 + 2 * hpair + hsel) * 64 + 2 * r); const float gn0 = gnorm[col], gn1 = gnorm[col + 1];
;         const unsigned voB = (tb * 1024u + 512u + col) * 2u;
; #pragma unroll
;         for (int i = 0; i < 16; ++i) { const unsigned w = ypk[hsel][i]; const float sn = ssq[i];
;             __builtin_amdgcn_raw_buffer_store_b32(pkbf(__uint_as_float(w << 16) * sn * gn0, __uint_as_float(w & 0xffff0000u) * sn * gn1), rsB, (int)voB, ((i & 3) + 8 * (i >> 2)) * 2048, 16); }
;     }
;     __syncthreads();
; __global__ void __launch_bounds__(NTHR, 2) k_main(Args a) {
;     ...
;             asm volatile("s_waitcnt vmcnt(0)" ::: "memory");
;             __syncthreads();
;             if (tid == 0) { __builtin_amdgcn_fence(__ATOMIC_RELEASE, "agent"); asm volatile("s_waitcnt vmcnt(0)" ::: "memory"); (void)xb_add(&((unsigned*)ws)[10240 + 16 * (u >> 2)], 1u); (void)xb_add(&((unsigned*)ws)[14336], 1u); }
	v_writelane_b32 v235, s26, 46
	v_writelane_b32 v235, s27, 47
	s_nop 0
	v_pk_mul_f32 v[36:37], v[36:37], v[34:35]
	s_nop 0
	v_cvt_pk_bf16_f32 v3, v36, v37
	v_lshlrev_b32_e32 v36, 16, v39
	v_and_b32_e32 v37, 0xffff0000, v39
	v_pk_mul_f32 v[36:37], v[8:9], v[36:37] op_sel_hi:[0,1]
	v_pk_mul_f32 v[36:37], v[36:37], v[34:35]
	buffer_store_dword v3, v5, s[4:7], 0 offen sc1
	v_cvt_pk_bf16_f32 v3, v36, v37
	v_lshlrev_b32_e32 v36, 16, v19
	v_and_b32_e32 v37, 0xffff0000, v19
	v_pk_mul_f32 v[36:37], v[10:11], v[36:37] op_sel_hi:[0,1]
	v_pk_mul_f32 v[36:37], v[36:37], v[34:35]
	buffer_store_dword v3, v5, s[4:7], s46 offen sc1
	v_cvt_pk_bf16_f32 v3, v36, v37
	v_lshlrev_b32_e32 v36, 16, v38
	v_and_b32_e32 v37, 0xffff0000, v38
	v_pk_mul_f32 v[36:37], v[6:7], v[36:37] op_sel_hi:[0,1]
	v_pk_mul_f32 v[36:37], v[36:37], v[34:35]
	buffer_store_dword v3, v5, s[4:7], s48 offen sc1
	v_cvt_pk_bf16_f32 v3, v36, v37
	v_lshlrev_b32_e32 v36, 16, v33
	v_and_b32_e32 v37, 0xffff0000, v33
	buffer_store_dword v3, v5, s[4:7], s56 offen sc1
	v_pk_mul_f32 v[2:3], v[2:3], v[36:37] op_sel_hi:[0,1]
	v_pk_mul_f32 v[2:3], v[2:3], v[34:35]
	s_nop 0
	v_cvt_pk_bf16_f32 v2, v2, v3
	buffer_store_dword v2, v5, s[4:7], s62 offen sc1
	v_lshlrev_b32_e32 v2, 16, v7
	v_and_b32_e32 v3, 0xffff0000, v7
	v_pk_mul_f32 v[2:3], v[14:15], v[2:3] op_sel_hi:[0,1]
	v_pk_mul_f32 v[2:3], v[2:3], v[34:35]
	s_nop 0
	v_cvt_pk_bf16_f32 v2, v2, v3
	buffer_store_dword v2, v5, s[4:7], s82 offen sc1
	v_lshlrev_b32_e32 v2, 16, v23
	v_and_b32_e32 v3, 0xffff0000, v23
	v_pk_mul_f32 v[2:3], v[30:31], v[2:3] op_sel_hi:[0,1]
	v_pk_mul_f32 v[2:3], v[2:3], v[34:35]
	s_nop 0
	v_cvt_pk_bf16_f32 v2, v2, v3
	buffer_store_dword v2, v5, s[4:7], s93 offen sc1
	v_lshlrev_b32_e32 v2, 16, v9
	v_and_b32_e32 v3, 0xffff0000, v9
	v_pk_mul_f32 v[2:3], v[22:23], v[2:3] op_sel_hi:[0,1]
	v_pk_mul_f32 v[2:3], v[2:3], v[34:35]
	s_nop 0
	v_cvt_pk_bf16_f32 v2, v2, v3
	buffer_store_dword v2, v5, s[4:7], s20 offen sc1
	v_lshlrev_b32_e32 v2, 16, v25
	v_and_b32_e32 v3, 0xffff0000, v25
	v_pk_mul_f32 v[2:3], v[32:33], v[2:3] op_sel_hi:[0,1]
	v_pk_mul_f32 v[2:3], v[2:3], v[34:35]
	s_nop 0
	v_cvt_pk_bf16_f32 v2, v2, v3
	buffer_store_dword v2, v5, s[4:7], s84 offen sc1
	v_lshlrev_b32_e32 v2, 16, v11
	v_and_b32_e32 v3, 0xffff0000, v11
	v_pk_mul_f32 v[2:3], v[24:25], v[2:3] op_sel_hi:[0,1]
	v_pk_mul_f32 v[2:3], v[2:3], v[34:35]
	s_nop 0
	v_cvt_pk_bf16_f32 v2, v2, v3
	buffer_store_dword v2, v5, s[4:7], s28 offen sc1
	v_lshlrev_b32_e32 v2, 16, v27
	v_and_b32_e32 v3, 0xffff0000, v27
	v_pk_mul_f32 v[2:3], v[26:27], v[2:3] op_sel_hi:[0,1]
	v_pk_mul_f32 v[2:3], v[2:3], v[34:35]
	s_nop 0
	v_cvt_pk_bf16_f32 v2, v2, v3
	buffer_store_dword v2, v5, s[4:7], s63 offen sc1
	v_lshlrev_b32_e32 v2, 16, v13
	v_and_b32_e32 v3, 0xffff0000, v13
	v_pk_mul_f32 v[2:3], v[16:17], v[2:3] op_sel_hi:[0,1]
	v_pk_mul_f32 v[2:3], v[2:3], v[34:35]
	s_nop 0
	v_cvt_pk_bf16_f32 v2, v2, v3
	buffer_store_dword v2, v5, s[4:7], s37 offen sc1
	v_lshlrev_b32_e32 v2, 16, v29
	v_and_b32_e32 v3, 0xffff0000, v29
	v_pk_mul_f32 v[2:3], v[28:29], v[2:3] op_sel_hi:[0,1]
	v_pk_mul_f32 v[2:3], v[2:3], v[34:35]
	s_nop 0
	v_cvt_pk_bf16_f32 v2, v2, v3
	buffer_store_dword v2, v5, s[4:7], s40 offen sc1
	v_lshlrev_b32_e32 v2, 16, v15
	v_and_b32_e32 v3, 0xffff0000, v15
	v_pk_mul_f32 v[2:3], v[18:19], v[2:3] op_sel_hi:[0,1]
	v_pk_mul_f32 v[2:3], v[2:3], v[34:35]
	s_nop 0
	v_cvt_pk_bf16_f32 v2, v2, v3
	buffer_store_dword v2, v5, s[4:7], s43 offen sc1
	v_lshlrev_b32_e32 v2, 16, v31
	v_and_b32_e32 v3, 0xffff0000, v31
	v_pk_mul_f32 v[2:3], v[20:21], v[2:3] op_sel_hi:[0,1]
	v_pk_mul_f32 v[2:3], v[2:3], v[34:35]
	s_nop 0
	v_cvt_pk_bf16_f32 v2, v2, v3
	buffer_store_dword v2, v5, s[4:7], s47 offen sc1
	v_lshlrev_b32_e32 v2, 16, v17
	v_and_b32_e32 v3, 0xffff0000, v17
	v_pk_mul_f32 v[2:3], v[4:5], v[2:3] op_sel_hi:[0,1]
	v_pk_mul_f32 v[2:3], v[2:3], v[34:35]
	s_nop 0
	v_cvt_pk_bf16_f32 v2, v2, v3
	buffer_store_dword v2, v5, s[4:7], s59 offen sc1
	s_barrier
	s_waitcnt vmcnt(0)
	s_barrier
	s_and_saveexec_b64 s[6:7], s[0:1]
	s_cbranch_execz .LBB0_465
	s_mov_b64 s[24:25], exec
	buffer_wbl2 sc1
	s_waitcnt vmcnt(0)
	s_waitcnt vmcnt(0)
	v_mbcnt_lo_u32_b32 v2, s24, 0
	v_mbcnt_hi_u32_b32 v2, s25, v2
	v_cmp_eq_u32_e64 s[4:5], 0, v2
	s_and_saveexec_b64 s[26:27], s[4:5]
	s_cbranch_execz .LBB0_471
	s_and_b32 s4, s30, -16
	s_ashr_i32 s5, s4, 31
	s_lshl_b64 s[4:5], s[4:5], 2
	s_add_u32 s4, s90, s4
	s_addc_u32 s5, s91, s5
	s_bcnt1_i32_b64 s24, s[24:25]
	v_mov_b32_e32 v2, s24
	global_atomic_add v162, v2, s[4:5]

; __device__ __forceinline__ unsigned xb_ld(unsigned* p)              { return __hip_atomic_load(p, __ATOMIC_RELAXED, __HIP_MEMORY_SCOPE_AGENT); }
; #define XB_SPIN(cond, bar) do { unsigned _sp = 0; while (cond) { __builtin_amdgcn_s_sleep(1); \
;     if ((++_sp & 255u) == 0u) { if (xb_ld(&(bar)[XB_TMO])) break; if (_sp > XB_SPIN_CAP) { atomicAdd(&(bar)[XB_TMO], 1u); break; } } } } while (0)
; __global__ void __launch_bounds__(NTHR, 2) k_main(Args a) {
;     ...
;           if (tid == 0) { pg8::Unit u; for (int i = 0; S.next(i, u); ++i) { unsigned* cw = &((unsigned*)ws)[6144 + 16 * u.pm]; XB_SPIN(xb_ld(cw) < 4u, (unsigned*)ws); }
;               XB_SPIN(xb_ld(&((unsigned*)ws)[14336]) < 256u, (unsigned*)ws);
;               __builtin_amdgcn_fence(__ATOMIC_ACQUIRE, "agent"); asm volatile("s_waitcnt vmcnt(0)" ::: "memory"); }
.LBB0_597:
	s_movk_i32 s3, 0xff
	s_add_u32 s6, s90, 0xe000
	s_addc_u32 s7, s91, 0
	s_waitcnt vmcnt(0)
	v_mov_b32_e32 v1, v8
	v_cmp_lt_u32_e32 vcc, s3, v1
	s_cbranch_vccnz .LBB0_610
	s_mov_b32 s14, 1
	v_mov_b32_e32 v1, 0
	s_branch .LBB0_600
